# final norm phase software-pipelined: 4 rows per trip, loads one trip ahead, counted waits, saddr addressing
# baseline (speedup 1.0000x reference)
; __device__ __forceinline__ float bflo(unsigned w) { return __uint_as_float(w << 16); }
; __device__ __forceinline__ float bfhi(unsigned w) { return __uint_as_float(w & 0xffff0000u); }
; __device__ __forceinline__ float rstd_row(const float* ss, int row) { const f32x4* p = (const f32x4*)(ss + (size_t)row * 16); const f32x4 a = p[0], b = p[1], c = p[2], d = p[3];
;     const float s = (((a[0] + a[1]) + (a[2] + a[3])) + ((b[0] + b[1]) + (b[2] + b[3]))) + (((c[0] + c[1]) + (c[2] + c[3])) + ((d[0] + d[1]) + (d[2] + d[3]))); return __builtin_amdgcn_rsqf(s * (1.f / 1024.f) + EPS); }
; __device__ __forceinline__ void final_norm_phase(const Frame& F, const bf16* h, const float* ssq, const float* gain, float* out) {
;     for (int it = F.bx * NTHR + F.tid; it < M * 128; it += F.G * NTHR) { const int row = it >> 7, c8 = (it & 127) * 8; const float rs = rstd_row(ssq, row);
;         const v4u w = *(const v4u*)(h + (size_t)row * DM_ + c8); const f32x4 g0 = *(const f32x4*)(gain + c8), g1 = *(const f32x4*)(gain + c8 + 4);
;         float* o = out + (size_t)row * DM_ + c8;
;         __builtin_nontemporal_store((f32x4){bflo(w.x) * rs * g0[0], bfhi(w.x) * rs * g0[1], bflo(w.y) * rs * g0[2], bfhi(w.y) * rs * g0[3]}, (f32x4*)o);
;         __builtin_nontemporal_store((f32x4){bflo(w.z) * rs * g1[0], bfhi(w.z) * rs * g1[1], bflo(w.w) * rs * g1[2], bfhi(w.w) * rs * g1[3]}, (f32x4*)(o + 4)); }
; }
.LBB0_1841:
	s_cmp_lt_i32 s80, 18
	s_cselect_b64 s[0:1], -1, 0
	s_cmp_gt_i32 s81, 17
	s_cselect_b64 s[2:3], -1, 0
	s_and_b64 s[0:1], s[0:1], s[2:3]
	s_andn2_b64 vcc, exec, s[0:1]
	s_cbranch_vccnz .LBB0_1845
	s_cmp_lg_u32 s82, 0x100
	s_cbranch_scc1 .Lfn_orig
	s_load_dwordx2 s[0:1], s[74:75], 0xe0
	v_and_b32_e32 v1, 0x7f, v0
	v_lshrrev_b32_e32 v2, 7, v0
	v_lshl_add_u32 v2, s96, 2, v2
	v_lshlrev_b32_e32 v3, 5, v1
	v_lshlrev_b32_e32 v4, 4, v1
	v_lshl_add_u32 v4, v2, 11, v4
	v_lshlrev_b32_e32 v5, 6, v2
	v_lshl_add_u32 v6, v2, 12, v3
	v_mov_b32_e32 v7, 0x358637bd
	s_add_u32 s4, s78, 0x7c00000
	s_addc_u32 s5, s79, 0
	s_add_u32 s6, s78, 0x5800000
	s_addc_u32 s7, s79, 0
	s_mov_b32 s8, s76
	s_mov_b32 s9, s77
	s_waitcnt lgkmcnt(0)
	global_load_dwordx4 v[8:11], v3, s[0:1]
	global_load_dwordx4 v[12:15], v3, s[0:1] offset:16
	global_load_dwordx4 v[16:19], v5, s[6:7]
	global_load_dwordx4 v[20:23], v5, s[6:7] offset:16
	global_load_dwordx4 v[24:27], v5, s[6:7] offset:32
	global_load_dwordx4 v[28:31], v5, s[6:7] offset:48
	global_load_dwordx4 v[32:35], v4, s[4:5]
	s_add_u32 s4, s4, 0x200000
	s_addc_u32 s5, s5, 0
	s_add_u32 s6, s6, 0x10000
	s_addc_u32 s7, s7, 0
	global_load_dwordx4 v[36:39], v5, s[6:7]
	global_load_dwordx4 v[40:43], v5, s[6:7] offset:16
	global_load_dwordx4 v[44:47], v5, s[6:7] offset:32
	global_load_dwordx4 v[48:51], v5, s[6:7] offset:48
	global_load_dwordx4 v[52:55], v4, s[4:5]
	s_add_u32 s4, s4, 0x200000
	s_addc_u32 s5, s5, 0
	s_add_u32 s6, s6, 0x10000
	s_addc_u32 s7, s7, 0
	global_load_dwordx4 v[56:59], v5, s[6:7]
	global_load_dwordx4 v[60:63], v5, s[6:7] offset:16
	global_load_dwordx4 v[64:67], v5, s[6:7] offset:32
	global_load_dwordx4 v[68:71], v5, s[6:7] offset:48
	global_load_dwordx4 v[72:75], v4, s[4:5]
	s_add_u32 s4, s4, 0x200000
	s_addc_u32 s5, s5, 0
	s_add_u32 s6, s6, 0x10000
	s_addc_u32 s7, s7, 0
	global_load_dwordx4 v[76:79], v5, s[6:7]
	global_load_dwordx4 v[80:83], v5, s[6:7] offset:16
	global_load_dwordx4 v[84:87], v5, s[6:7] offset:32
	global_load_dwordx4 v[88:91], v5, s[6:7] offset:48
	global_load_dwordx4 v[92:95], v4, s[4:5]
	s_add_u32 s4, s4, 0x200000
	s_addc_u32 s5, s5, 0
	s_add_u32 s6, s6, 0x10000
	s_addc_u32 s7, s7, 0
	global_load_dwordx4 v[96:99], v5, s[6:7]
	global_load_dwordx4 v[100:103], v5, s[6:7] offset:16
	global_load_dwordx4 v[104:107], v5, s[6:7] offset:32
	global_load_dwordx4 v[108:111], v5, s[6:7] offset:48
	global_load_dwordx4 v[112:115], v4, s[4:5]
	s_add_u32 s4, s4, 0x200000
	s_addc_u32 s5, s5, 0
	s_add_u32 s6, s6, 0x10000
	s_addc_u32 s7, s7, 0
	global_load_dwordx4 v[116:119], v5, s[6:7]
	global_load_dwordx4 v[120:123], v5, s[6:7] offset:16
	global_load_dwordx4 v[124:127], v5, s[6:7] offset:32
	global_load_dwordx4 v[128:131], v5, s[6:7] offset:48
	global_load_dwordx4 v[132:135], v4, s[4:5]
	s_add_u32 s4, s4, 0x200000
	s_addc_u32 s5, s5, 0
	s_add_u32 s6, s6, 0x10000
	s_addc_u32 s7, s7, 0
	global_load_dwordx4 v[136:139], v5, s[6:7]
	global_load_dwordx4 v[140:143], v5, s[6:7] offset:16
	global_load_dwordx4 v[144:147], v5, s[6:7] offset:32
	global_load_dwordx4 v[148:151], v5, s[6:7] offset:48
	global_load_dwordx4 v[152:155], v4, s[4:5]
	s_add_u32 s4, s4, 0x200000
	s_addc_u32 s5, s5, 0
	s_add_u32 s6, s6, 0x10000
	s_addc_u32 s7, s7, 0
	global_load_dwordx4 v[156:159], v5, s[6:7]
	global_load_dwordx4 v[160:163], v5, s[6:7] offset:16
	global_load_dwordx4 v[164:167], v5, s[6:7] offset:32
	global_load_dwordx4 v[168:171], v5, s[6:7] offset:48
	global_load_dwordx4 v[172:175], v4, s[4:5]
	s_add_u32 s4, s4, 0x200000
	s_addc_u32 s5, s5, 0
	s_add_u32 s6, s6, 0x10000
	s_addc_u32 s7, s7, 0
	s_waitcnt vmcnt(20)
	v_add_f32_e32 v16, v16, v17
	v_add_f32_e32 v18, v18, v19
	v_add_f32_e32 v20, v20, v21
	v_add_f32_e32 v22, v22, v23
	v_add_f32_e32 v24, v24, v25
	v_add_f32_e32 v26, v26, v27
	v_add_f32_e32 v28, v28, v29
	v_add_f32_e32 v30, v30, v31
	v_add_f32_e32 v16, v16, v18
	v_add_f32_e32 v20, v20, v22
	v_add_f32_e32 v24, v24, v26
	v_add_f32_e32 v28, v28, v30
	v_add_f32_e32 v16, v16, v20
	v_add_f32_e32 v24, v24, v28
	v_add_f32_e32 v16, v16, v24
	v_fmamk_f32 v16, v16, 0x3a800000, v7
	v_rsq_f32_e32 v16, v16
	v_lshlrev_b32_e32 v20, 16, v32
	v_and_b32_e32 v21, 0xffff0000, v32
	v_lshlrev_b32_e32 v22, 16, v33
	v_and_b32_e32 v23, 0xffff0000, v33
	v_lshlrev_b32_e32 v24, 16, v34
	v_and_b32_e32 v25, 0xffff0000, v34
	v_lshlrev_b32_e32 v26, 16, v35
	v_and_b32_e32 v27, 0xffff0000, v35
	s_nop 0
	v_mul_f32_e32 v20, v16, v20
	v_mul_f32_e32 v21, v16, v21
	v_mul_f32_e32 v22, v16, v22
	v_mul_f32_e32 v23, v16, v23
	v_mul_f32_e32 v24, v16, v24
	v_mul_f32_e32 v25, v16, v25
	v_mul_f32_e32 v26, v16, v26
	v_mul_f32_e32 v27, v16, v27
	v_mul_f32_e32 v20, v8, v20
	v_mul_f32_e32 v21, v9, v21
	v_mul_f32_e32 v22, v10, v22
	v_mul_f32_e32 v23, v11, v23
	v_mul_f32_e32 v24, v12, v24
	v_mul_f32_e32 v25, v13, v25
	v_mul_f32_e32 v26, v14, v26
	v_mul_f32_e32 v27, v15, v27
	global_store_dwordx4 v6, v[20:23], s[8:9] nt
	global_store_dwordx4 v6, v[24:27], s[8:9] offset:16 nt
	s_add_u32 s8, s8, 0x400000
	s_addc_u32 s9, s9, 0
	v_add_f32_e32 v36, v36, v37
	v_add_f32_e32 v38, v38, v39
	v_add_f32_e32 v40, v40, v41
	v_add_f32_e32 v42, v42, v43
	v_add_f32_e32 v44, v44, v45
	v_add_f32_e32 v46, v46, v47
	v_add_f32_e32 v48, v48, v49
	v_add_f32_e32 v50, v50, v51
	v_add_f32_e32 v36, v36, v38
	v_add_f32_e32 v40, v40, v42
	v_add_f32_e32 v44, v44, v46
	v_add_f32_e32 v48, v48, v50
	v_add_f32_e32 v36, v36, v40
	v_add_f32_e32 v44, v44, v48
	v_add_f32_e32 v36, v36, v44
	v_fmamk_f32 v36, v36, 0x3a800000, v7
	v_rsq_f32_e32 v36, v36
	v_lshlrev_b32_e32 v40, 16, v52
	v_and_b32_e32 v41, 0xffff0000, v52
	v_lshlrev_b32_e32 v42, 16, v53
	v_and_b32_e32 v43, 0xffff0000, v53
	v_lshlrev_b32_e32 v44, 16, v54
; __device__ __forceinline__ float bflo(unsigned w) { return __uint_as_float(w << 16); }
; __device__ __forceinline__ float bfhi(unsigned w) { return __uint_as_float(w & 0xffff0000u); }
; __device__ __forceinline__ float rstd_row(const float* ss, int row) { const f32x4* p = (const f32x4*)(ss + (size_t)row * 16); const f32x4 a = p[0], b = p[1], c = p[2], d = p[3];
;     const float s = (((a[0] + a[1]) + (a[2] + a[3])) + ((b[0] + b[1]) + (b[2] + b[3]))) + (((c[0] + c[1]) + (c[2] + c[3])) + ((d[0] + d[1]) + (d[2] + d[3]))); return __builtin_amdgcn_rsqf(s * (1.f / 1024.f) + EPS); }
; __device__ __forceinline__ void final_norm_phase(const Frame& F, const bf16* h, const float* ssq, const float* gain, float* out) {
;     for (int it = F.bx * NTHR + F.tid; it < M * 128; it += F.G * NTHR) { const int row = it >> 7, c8 = (it & 127) * 8; const float rs = rstd_row(ssq, row);
;         const v4u w = *(const v4u*)(h + (size_t)row * DM_ + c8); const f32x4 g0 = *(const f32x4*)(gain + c8), g1 = *(const f32x4*)(gain + c8 + 4);
;         float* o = out + (size_t)row * DM_ + c8;
;         __builtin_nontemporal_store((f32x4){bflo(w.x) * rs * g0[0], bfhi(w.x) * rs * g0[1], bflo(w.y) * rs * g0[2], bfhi(w.y) * rs * g0[3]}, (f32x4*)o);
;         __builtin_nontemporal_store((f32x4){bflo(w.z) * rs * g1[0], bfhi(w.z) * rs * g1[1], bflo(w.w) * rs * g1[2], bfhi(w.w) * rs * g1[3]}, (f32x4*)(o + 4)); }
; }
	v_and_b32_e32 v45, 0xffff0000, v54
	v_lshlrev_b32_e32 v46, 16, v55
	v_and_b32_e32 v47, 0xffff0000, v55
	s_nop 0
	v_mul_f32_e32 v40, v36, v40
	v_mul_f32_e32 v41, v36, v41
	v_mul_f32_e32 v42, v36, v42
	v_mul_f32_e32 v43, v36, v43
	v_mul_f32_e32 v44, v36, v44
	v_mul_f32_e32 v45, v36, v45
	v_mul_f32_e32 v46, v36, v46
	v_mul_f32_e32 v47, v36, v47
	v_mul_f32_e32 v40, v8, v40
	v_mul_f32_e32 v41, v9, v41
	v_mul_f32_e32 v42, v10, v42
	v_mul_f32_e32 v43, v11, v43
	v_mul_f32_e32 v44, v12, v44
	v_mul_f32_e32 v45, v13, v45
	v_mul_f32_e32 v46, v14, v46
	v_mul_f32_e32 v47, v15, v47
	global_store_dwordx4 v6, v[40:43], s[8:9] nt
	global_store_dwordx4 v6, v[44:47], s[8:9] offset:16 nt
	s_add_u32 s8, s8, 0x400000
	s_addc_u32 s9, s9, 0
	v_add_f32_e32 v56, v56, v57
	v_add_f32_e32 v58, v58, v59
	v_add_f32_e32 v60, v60, v61
	v_add_f32_e32 v62, v62, v63
	v_add_f32_e32 v64, v64, v65
	v_add_f32_e32 v66, v66, v67
	v_add_f32_e32 v68, v68, v69
	v_add_f32_e32 v70, v70, v71
	v_add_f32_e32 v56, v56, v58
	v_add_f32_e32 v60, v60, v62
	v_add_f32_e32 v64, v64, v66
	v_add_f32_e32 v68, v68, v70
	v_add_f32_e32 v56, v56, v60
	v_add_f32_e32 v64, v64, v68
	v_add_f32_e32 v56, v56, v64
	v_fmamk_f32 v56, v56, 0x3a800000, v7
	v_rsq_f32_e32 v56, v56
	v_lshlrev_b32_e32 v60, 16, v72
	v_and_b32_e32 v61, 0xffff0000, v72
	v_lshlrev_b32_e32 v62, 16, v73
	v_and_b32_e32 v63, 0xffff0000, v73
	v_lshlrev_b32_e32 v64, 16, v74
	v_and_b32_e32 v65, 0xffff0000, v74
	v_lshlrev_b32_e32 v66, 16, v75
	v_and_b32_e32 v67, 0xffff0000, v75
	s_nop 0
	v_mul_f32_e32 v60, v56, v60
	v_mul_f32_e32 v61, v56, v61
	v_mul_f32_e32 v62, v56, v62
	v_mul_f32_e32 v63, v56, v63
	v_mul_f32_e32 v64, v56, v64
	v_mul_f32_e32 v65, v56, v65
	v_mul_f32_e32 v66, v56, v66
	v_mul_f32_e32 v67, v56, v67
	v_mul_f32_e32 v60, v8, v60
	v_mul_f32_e32 v61, v9, v61
	v_mul_f32_e32 v62, v10, v62
	v_mul_f32_e32 v63, v11, v63
	v_mul_f32_e32 v64, v12, v64
	v_mul_f32_e32 v65, v13, v65
	v_mul_f32_e32 v66, v14, v66
	v_mul_f32_e32 v67, v15, v67
	global_store_dwordx4 v6, v[60:63], s[8:9] nt
	global_store_dwordx4 v6, v[64:67], s[8:9] offset:16 nt
	s_add_u32 s8, s8, 0x400000
	s_addc_u32 s9, s9, 0
	v_add_f32_e32 v76, v76, v77
	v_add_f32_e32 v78, v78, v79
	v_add_f32_e32 v80, v80, v81
	v_add_f32_e32 v82, v82, v83
	v_add_f32_e32 v84, v84, v85
	v_add_f32_e32 v86, v86, v87
	v_add_f32_e32 v88, v88, v89
	v_add_f32_e32 v90, v90, v91
	v_add_f32_e32 v76, v76, v78
	v_add_f32_e32 v80, v80, v82
	v_add_f32_e32 v84, v84, v86
	v_add_f32_e32 v88, v88, v90
	v_add_f32_e32 v76, v76, v80
	v_add_f32_e32 v84, v84, v88
	v_add_f32_e32 v76, v76, v84
	v_fmamk_f32 v76, v76, 0x3a800000, v7
	v_rsq_f32_e32 v76, v76
	v_lshlrev_b32_e32 v80, 16, v92
	v_and_b32_e32 v81, 0xffff0000, v92
	v_lshlrev_b32_e32 v82, 16, v93
	v_and_b32_e32 v83, 0xffff0000, v93
	v_lshlrev_b32_e32 v84, 16, v94
	v_and_b32_e32 v85, 0xffff0000, v94
	v_lshlrev_b32_e32 v86, 16, v95
	v_and_b32_e32 v87, 0xffff0000, v95
	s_nop 0
	v_mul_f32_e32 v80, v76, v80
	v_mul_f32_e32 v81, v76, v81
	v_mul_f32_e32 v82, v76, v82
	v_mul_f32_e32 v83, v76, v83
	v_mul_f32_e32 v84, v76, v84
	v_mul_f32_e32 v85, v76, v85
	v_mul_f32_e32 v86, v76, v86
	v_mul_f32_e32 v87, v76, v87
	v_mul_f32_e32 v80, v8, v80
	v_mul_f32_e32 v81, v9, v81
	v_mul_f32_e32 v82, v10, v82
	v_mul_f32_e32 v83, v11, v83
	v_mul_f32_e32 v84, v12, v84
	v_mul_f32_e32 v85, v13, v85
	v_mul_f32_e32 v86, v14, v86
	v_mul_f32_e32 v87, v15, v87
	global_store_dwordx4 v6, v[80:83], s[8:9] nt
	global_store_dwordx4 v6, v[84:87], s[8:9] offset:16 nt
	s_add_u32 s8, s8, 0x400000
	s_addc_u32 s9, s9, 0
	global_load_dwordx4 v[16:19], v5, s[6:7]
	global_load_dwordx4 v[20:23], v5, s[6:7] offset:16
	global_load_dwordx4 v[24:27], v5, s[6:7] offset:32
	global_load_dwordx4 v[28:31], v5, s[6:7] offset:48
	global_load_dwordx4 v[32:35], v4, s[4:5]
	s_add_u32 s4, s4, 0x200000
	s_addc_u32 s5, s5, 0
	s_add_u32 s6, s6, 0x10000
	s_addc_u32 s7, s7, 0
	global_load_dwordx4 v[36:39], v5, s[6:7]
	global_load_dwordx4 v[40:43], v5, s[6:7] offset:16
	global_load_dwordx4 v[44:47], v5, s[6:7] offset:32
	global_load_dwordx4 v[48:51], v5, s[6:7] offset:48
	global_load_dwordx4 v[52:55], v4, s[4:5]
	s_add_u32 s4, s4, 0x200000
	s_addc_u32 s5, s5, 0
	s_add_u32 s6, s6, 0x10000
	s_addc_u32 s7, s7, 0
	global_load_dwordx4 v[56:59], v5, s[6:7]
	global_load_dwordx4 v[60:63], v5, s[6:7] offset:16
	global_load_dwordx4 v[64:67], v5, s[6:7] offset:32
	global_load_dwordx4 v[68:71], v5, s[6:7] offset:48
	global_load_dwordx4 v[72:75], v4, s[4:5]
	s_add_u32 s4, s4, 0x200000
	s_addc_u32 s5, s5, 0
	s_add_u32 s6, s6, 0x10000
	s_addc_u32 s7, s7, 0
	global_load_dwordx4 v[76:79], v5, s[6:7]
	global_load_dwordx4 v[80:83], v5, s[6:7] offset:16
	global_load_dwordx4 v[84:87], v5, s[6:7] offset:32
	global_load_dwordx4 v[88:91], v5, s[6:7] offset:48
	global_load_dwordx4 v[92:95], v4, s[4:5]
	s_add_u32 s4, s4, 0x200000
	s_addc_u32 s5, s5, 0
	s_add_u32 s6, s6, 0x10000
	s_addc_u32 s7, s7, 0
	s_waitcnt vmcnt(28)
; __device__ __forceinline__ float bflo(unsigned w) { return __uint_as_float(w << 16); }
; __device__ __forceinline__ float bfhi(unsigned w) { return __uint_as_float(w & 0xffff0000u); }
; __device__ __forceinline__ float rstd_row(const float* ss, int row) { const f32x4* p = (const f32x4*)(ss + (size_t)row * 16); const f32x4 a = p[0], b = p[1], c = p[2], d = p[3];
;     const float s = (((a[0] + a[1]) + (a[2] + a[3])) + ((b[0] + b[1]) + (b[2] + b[3]))) + (((c[0] + c[1]) + (c[2] + c[3])) + ((d[0] + d[1]) + (d[2] + d[3]))); return __builtin_amdgcn_rsqf(s * (1.f / 1024.f) + EPS); }
; __device__ __forceinline__ void final_norm_phase(const Frame& F, const bf16* h, const float* ssq, const float* gain, float* out) {
;     for (int it = F.bx * NTHR + F.tid; it < M * 128; it += F.G * NTHR) { const int row = it >> 7, c8 = (it & 127) * 8; const float rs = rstd_row(ssq, row);
;         const v4u w = *(const v4u*)(h + (size_t)row * DM_ + c8); const f32x4 g0 = *(const f32x4*)(gain + c8), g1 = *(const f32x4*)(gain + c8 + 4);
;         float* o = out + (size_t)row * DM_ + c8;
;         __builtin_nontemporal_store((f32x4){bflo(w.x) * rs * g0[0], bfhi(w.x) * rs * g0[1], bflo(w.y) * rs * g0[2], bfhi(w.y) * rs * g0[3]}, (f32x4*)o);
;         __builtin_nontemporal_store((f32x4){bflo(w.z) * rs * g1[0], bfhi(w.z) * rs * g1[1], bflo(w.w) * rs * g1[2], bfhi(w.w) * rs * g1[3]}, (f32x4*)(o + 4)); }
; }
	v_add_f32_e32 v96, v96, v97
	v_add_f32_e32 v98, v98, v99
	v_add_f32_e32 v100, v100, v101
	v_add_f32_e32 v102, v102, v103
	v_add_f32_e32 v104, v104, v105
	v_add_f32_e32 v106, v106, v107
	v_add_f32_e32 v108, v108, v109
	v_add_f32_e32 v110, v110, v111
	v_add_f32_e32 v96, v96, v98
	v_add_f32_e32 v100, v100, v102
	v_add_f32_e32 v104, v104, v106
	v_add_f32_e32 v108, v108, v110
	v_add_f32_e32 v96, v96, v100
	v_add_f32_e32 v104, v104, v108
	v_add_f32_e32 v96, v96, v104
	v_fmamk_f32 v96, v96, 0x3a800000, v7
	v_rsq_f32_e32 v96, v96
	v_lshlrev_b32_e32 v100, 16, v112
	v_and_b32_e32 v101, 0xffff0000, v112
	v_lshlrev_b32_e32 v102, 16, v113
	v_and_b32_e32 v103, 0xffff0000, v113
	v_lshlrev_b32_e32 v104, 16, v114
	v_and_b32_e32 v105, 0xffff0000, v114
	v_lshlrev_b32_e32 v106, 16, v115
	v_and_b32_e32 v107, 0xffff0000, v115
	s_nop 0
	v_mul_f32_e32 v100, v96, v100
	v_mul_f32_e32 v101, v96, v101
	v_mul_f32_e32 v102, v96, v102
	v_mul_f32_e32 v103, v96, v103
	v_mul_f32_e32 v104, v96, v104
	v_mul_f32_e32 v105, v96, v105
	v_mul_f32_e32 v106, v96, v106
	v_mul_f32_e32 v107, v96, v107
	v_mul_f32_e32 v100, v8, v100
	v_mul_f32_e32 v101, v9, v101
	v_mul_f32_e32 v102, v10, v102
	v_mul_f32_e32 v103, v11, v103
	v_mul_f32_e32 v104, v12, v104
	v_mul_f32_e32 v105, v13, v105
	v_mul_f32_e32 v106, v14, v106
	v_mul_f32_e32 v107, v15, v107
	global_store_dwordx4 v6, v[100:103], s[8:9] nt
	global_store_dwordx4 v6, v[104:107], s[8:9] offset:16 nt
	s_add_u32 s8, s8, 0x400000
	s_addc_u32 s9, s9, 0
	v_add_f32_e32 v116, v116, v117
	v_add_f32_e32 v118, v118, v119
	v_add_f32_e32 v120, v120, v121
	v_add_f32_e32 v122, v122, v123
	v_add_f32_e32 v124, v124, v125
	v_add_f32_e32 v126, v126, v127
	v_add_f32_e32 v128, v128, v129
	v_add_f32_e32 v130, v130, v131
	v_add_f32_e32 v116, v116, v118
	v_add_f32_e32 v120, v120, v122
	v_add_f32_e32 v124, v124, v126
	v_add_f32_e32 v128, v128, v130
	v_add_f32_e32 v116, v116, v120
	v_add_f32_e32 v124, v124, v128
	v_add_f32_e32 v116, v116, v124
	v_fmamk_f32 v116, v116, 0x3a800000, v7
	v_rsq_f32_e32 v116, v116
	v_lshlrev_b32_e32 v120, 16, v132
	v_and_b32_e32 v121, 0xffff0000, v132
	v_lshlrev_b32_e32 v122, 16, v133
	v_and_b32_e32 v123, 0xffff0000, v133
	v_lshlrev_b32_e32 v124, 16, v134
	v_and_b32_e32 v125, 0xffff0000, v134
	v_lshlrev_b32_e32 v126, 16, v135
	v_and_b32_e32 v127, 0xffff0000, v135
	s_nop 0
	v_mul_f32_e32 v120, v116, v120
	v_mul_f32_e32 v121, v116, v121
	v_mul_f32_e32 v122, v116, v122
	v_mul_f32_e32 v123, v116, v123
	v_mul_f32_e32 v124, v116, v124
	v_mul_f32_e32 v125, v116, v125
	v_mul_f32_e32 v126, v116, v126
	v_mul_f32_e32 v127, v116, v127
	v_mul_f32_e32 v120, v8, v120
	v_mul_f32_e32 v121, v9, v121
	v_mul_f32_e32 v122, v10, v122
	v_mul_f32_e32 v123, v11, v123
	v_mul_f32_e32 v124, v12, v124
	v_mul_f32_e32 v125, v13, v125
	v_mul_f32_e32 v126, v14, v126
	v_mul_f32_e32 v127, v15, v127
	global_store_dwordx4 v6, v[120:123], s[8:9] nt
	global_store_dwordx4 v6, v[124:127], s[8:9] offset:16 nt
	s_add_u32 s8, s8, 0x400000
	s_addc_u32 s9, s9, 0
	v_add_f32_e32 v136, v136, v137
	v_add_f32_e32 v138, v138, v139
	v_add_f32_e32 v140, v140, v141
	v_add_f32_e32 v142, v142, v143
	v_add_f32_e32 v144, v144, v145
	v_add_f32_e32 v146, v146, v147
	v_add_f32_e32 v148, v148, v149
	v_add_f32_e32 v150, v150, v151
	v_add_f32_e32 v136, v136, v138
	v_add_f32_e32 v140, v140, v142
	v_add_f32_e32 v144, v144, v146
	v_add_f32_e32 v148, v148, v150
	v_add_f32_e32 v136, v136, v140
	v_add_f32_e32 v144, v144, v148
	v_add_f32_e32 v136, v136, v144
	v_fmamk_f32 v136, v136, 0x3a800000, v7
	v_rsq_f32_e32 v136, v136
	v_lshlrev_b32_e32 v140, 16, v152
	v_and_b32_e32 v141, 0xffff0000, v152
	v_lshlrev_b32_e32 v142, 16, v153
	v_and_b32_e32 v143, 0xffff0000, v153
	v_lshlrev_b32_e32 v144, 16, v154
	v_and_b32_e32 v145, 0xffff0000, v154
	v_lshlrev_b32_e32 v146, 16, v155
	v_and_b32_e32 v147, 0xffff0000, v155
	s_nop 0
	v_mul_f32_e32 v140, v136, v140
	v_mul_f32_e32 v141, v136, v141
	v_mul_f32_e32 v142, v136, v142
	v_mul_f32_e32 v143, v136, v143
	v_mul_f32_e32 v144, v136, v144
	v_mul_f32_e32 v145, v136, v145
	v_mul_f32_e32 v146, v136, v146
	v_mul_f32_e32 v147, v136, v147
	v_mul_f32_e32 v140, v8, v140
	v_mul_f32_e32 v141, v9, v141
	v_mul_f32_e32 v142, v10, v142
	v_mul_f32_e32 v143, v11, v143
	v_mul_f32_e32 v144, v12, v144
	v_mul_f32_e32 v145, v13, v145
	v_mul_f32_e32 v146, v14, v146
	v_mul_f32_e32 v147, v15, v147
	global_store_dwordx4 v6, v[140:143], s[8:9] nt
	global_store_dwordx4 v6, v[144:147], s[8:9] offset:16 nt
	s_add_u32 s8, s8, 0x400000
	s_addc_u32 s9, s9, 0
	v_add_f32_e32 v156, v156, v157
	v_add_f32_e32 v158, v158, v159
	v_add_f32_e32 v160, v160, v161
	v_add_f32_e32 v162, v162, v163
	v_add_f32_e32 v164, v164, v165
	v_add_f32_e32 v166, v166, v167
	v_add_f32_e32 v168, v168, v169
	v_add_f32_e32 v170, v170, v171
	v_add_f32_e32 v156, v156, v158
	v_add_f32_e32 v160, v160, v162
	v_add_f32_e32 v164, v164, v166
	v_add_f32_e32 v168, v168, v170
	v_add_f32_e32 v156, v156, v160
	v_add_f32_e32 v164, v164, v168
	v_add_f32_e32 v156, v156, v164
	v_fmamk_f32 v156, v156, 0x3a800000, v7
	v_rsq_f32_e32 v156, v156
	v_lshlrev_b32_e32 v160, 16, v172
	v_and_b32_e32 v161, 0xffff0000, v172
	v_lshlrev_b32_e32 v162, 16, v173
	v_and_b32_e32 v163, 0xffff0000, v173
	v_lshlrev_b32_e32 v164, 16, v174
	v_and_b32_e32 v165, 0xffff0000, v174
	v_lshlrev_b32_e32 v166, 16, v175
	v_and_b32_e32 v167, 0xffff0000, v175
	s_nop 0
	v_mul_f32_e32 v160, v156, v160
	v_mul_f32_e32 v161, v156, v161
	v_mul_f32_e32 v162, v156, v162
	v_mul_f32_e32 v163, v156, v163
	v_mul_f32_e32 v164, v156, v164
	v_mul_f32_e32 v165, v156, v165
	v_mul_f32_e32 v166, v156, v166
	v_mul_f32_e32 v167, v156, v167
	v_mul_f32_e32 v160, v8, v160
	v_mul_f32_e32 v161, v9, v161
; __device__ __forceinline__ float bflo(unsigned w) { return __uint_as_float(w << 16); }
; __device__ __forceinline__ float bfhi(unsigned w) { return __uint_as_float(w & 0xffff0000u); }
; __device__ __forceinline__ float rstd_row(const float* ss, int row) { const f32x4* p = (const f32x4*)(ss + (size_t)row * 16); const f32x4 a = p[0], b = p[1], c = p[2], d = p[3];
;     const float s = (((a[0] + a[1]) + (a[2] + a[3])) + ((b[0] + b[1]) + (b[2] + b[3]))) + (((c[0] + c[1]) + (c[2] + c[3])) + ((d[0] + d[1]) + (d[2] + d[3]))); return __builtin_amdgcn_rsqf(s * (1.f / 1024.f) + EPS); }
; __device__ __forceinline__ void final_norm_phase(const Frame& F, const bf16* h, const float* ssq, const float* gain, float* out) {
;     for (int it = F.bx * NTHR + F.tid; it < M * 128; it += F.G * NTHR) { const int row = it >> 7, c8 = (it & 127) * 8; const float rs = rstd_row(ssq, row);
;         const v4u w = *(const v4u*)(h + (size_t)row * DM_ + c8); const f32x4 g0 = *(const f32x4*)(gain + c8), g1 = *(const f32x4*)(gain + c8 + 4);
;         float* o = out + (size_t)row * DM_ + c8;
;         __builtin_nontemporal_store((f32x4){bflo(w.x) * rs * g0[0], bfhi(w.x) * rs * g0[1], bflo(w.y) * rs * g0[2], bfhi(w.y) * rs * g0[3]}, (f32x4*)o);
;         __builtin_nontemporal_store((f32x4){bflo(w.z) * rs * g1[0], bfhi(w.z) * rs * g1[1], bflo(w.w) * rs * g1[2], bfhi(w.w) * rs * g1[3]}, (f32x4*)(o + 4)); }
; }
	v_mul_f32_e32 v162, v10, v162
	v_mul_f32_e32 v163, v11, v163
	v_mul_f32_e32 v164, v12, v164
	v_mul_f32_e32 v165, v13, v165
	v_mul_f32_e32 v166, v14, v166
	v_mul_f32_e32 v167, v15, v167
	global_store_dwordx4 v6, v[160:163], s[8:9] nt
	global_store_dwordx4 v6, v[164:167], s[8:9] offset:16 nt
	s_add_u32 s8, s8, 0x400000
	s_addc_u32 s9, s9, 0
	global_load_dwordx4 v[96:99], v5, s[6:7]
	global_load_dwordx4 v[100:103], v5, s[6:7] offset:16
	global_load_dwordx4 v[104:107], v5, s[6:7] offset:32
	global_load_dwordx4 v[108:111], v5, s[6:7] offset:48
	global_load_dwordx4 v[112:115], v4, s[4:5]
	s_add_u32 s4, s4, 0x200000
	s_addc_u32 s5, s5, 0
	s_add_u32 s6, s6, 0x10000
	s_addc_u32 s7, s7, 0
	global_load_dwordx4 v[116:119], v5, s[6:7]
	global_load_dwordx4 v[120:123], v5, s[6:7] offset:16
	global_load_dwordx4 v[124:127], v5, s[6:7] offset:32
	global_load_dwordx4 v[128:131], v5, s[6:7] offset:48
	global_load_dwordx4 v[132:135], v4, s[4:5]
	s_add_u32 s4, s4, 0x200000
	s_addc_u32 s5, s5, 0
	s_add_u32 s6, s6, 0x10000
	s_addc_u32 s7, s7, 0
	global_load_dwordx4 v[136:139], v5, s[6:7]
	global_load_dwordx4 v[140:143], v5, s[6:7] offset:16
	global_load_dwordx4 v[144:147], v5, s[6:7] offset:32
	global_load_dwordx4 v[148:151], v5, s[6:7] offset:48
	global_load_dwordx4 v[152:155], v4, s[4:5]
	s_add_u32 s4, s4, 0x200000
	s_addc_u32 s5, s5, 0
	s_add_u32 s6, s6, 0x10000
	s_addc_u32 s7, s7, 0
	global_load_dwordx4 v[156:159], v5, s[6:7]
	global_load_dwordx4 v[160:163], v5, s[6:7] offset:16
	global_load_dwordx4 v[164:167], v5, s[6:7] offset:32
	global_load_dwordx4 v[168:171], v5, s[6:7] offset:48
	global_load_dwordx4 v[172:175], v4, s[4:5]
	s_add_u32 s4, s4, 0x200000
	s_addc_u32 s5, s5, 0
	s_add_u32 s6, s6, 0x10000
	s_addc_u32 s7, s7, 0
	s_waitcnt vmcnt(28)
	v_add_f32_e32 v16, v16, v17
	v_add_f32_e32 v18, v18, v19
	v_add_f32_e32 v20, v20, v21
	v_add_f32_e32 v22, v22, v23
	v_add_f32_e32 v24, v24, v25
	v_add_f32_e32 v26, v26, v27
	v_add_f32_e32 v28, v28, v29
	v_add_f32_e32 v30, v30, v31
	v_add_f32_e32 v16, v16, v18
	v_add_f32_e32 v20, v20, v22
	v_add_f32_e32 v24, v24, v26
	v_add_f32_e32 v28, v28, v30
	v_add_f32_e32 v16, v16, v20
	v_add_f32_e32 v24, v24, v28
	v_add_f32_e32 v16, v16, v24
	v_fmamk_f32 v16, v16, 0x3a800000, v7
	v_rsq_f32_e32 v16, v16
	v_lshlrev_b32_e32 v20, 16, v32
	v_and_b32_e32 v21, 0xffff0000, v32
	v_lshlrev_b32_e32 v22, 16, v33
	v_and_b32_e32 v23, 0xffff0000, v33
	v_lshlrev_b32_e32 v24, 16, v34
	v_and_b32_e32 v25, 0xffff0000, v34
	v_lshlrev_b32_e32 v26, 16, v35
	v_and_b32_e32 v27, 0xffff0000, v35
	s_nop 0
	v_mul_f32_e32 v20, v16, v20
	v_mul_f32_e32 v21, v16, v21
	v_mul_f32_e32 v22, v16, v22
	v_mul_f32_e32 v23, v16, v23
	v_mul_f32_e32 v24, v16, v24
	v_mul_f32_e32 v25, v16, v25
	v_mul_f32_e32 v26, v16, v26
	v_mul_f32_e32 v27, v16, v27
	v_mul_f32_e32 v20, v8, v20
	v_mul_f32_e32 v21, v9, v21
	v_mul_f32_e32 v22, v10, v22
	v_mul_f32_e32 v23, v11, v23
	v_mul_f32_e32 v24, v12, v24
	v_mul_f32_e32 v25, v13, v25
	v_mul_f32_e32 v26, v14, v26
	v_mul_f32_e32 v27, v15, v27
	global_store_dwordx4 v6, v[20:23], s[8:9] nt
	global_store_dwordx4 v6, v[24:27], s[8:9] offset:16 nt
	s_add_u32 s8, s8, 0x400000
	s_addc_u32 s9, s9, 0
	v_add_f32_e32 v36, v36, v37
	v_add_f32_e32 v38, v38, v39
	v_add_f32_e32 v40, v40, v41
	v_add_f32_e32 v42, v42, v43
	v_add_f32_e32 v44, v44, v45
	v_add_f32_e32 v46, v46, v47
	v_add_f32_e32 v48, v48, v49
	v_add_f32_e32 v50, v50, v51
	v_add_f32_e32 v36, v36, v38
	v_add_f32_e32 v40, v40, v42
	v_add_f32_e32 v44, v44, v46
	v_add_f32_e32 v48, v48, v50
	v_add_f32_e32 v36, v36, v40
	v_add_f32_e32 v44, v44, v48
	v_add_f32_e32 v36, v36, v44
	v_fmamk_f32 v36, v36, 0x3a800000, v7
	v_rsq_f32_e32 v36, v36
	v_lshlrev_b32_e32 v40, 16, v52
	v_and_b32_e32 v41, 0xffff0000, v52
	v_lshlrev_b32_e32 v42, 16, v53
	v_and_b32_e32 v43, 0xffff0000, v53
	v_lshlrev_b32_e32 v44, 16, v54
	v_and_b32_e32 v45, 0xffff0000, v54
	v_lshlrev_b32_e32 v46, 16, v55
	v_and_b32_e32 v47, 0xffff0000, v55
	s_nop 0
	v_mul_f32_e32 v40, v36, v40
	v_mul_f32_e32 v41, v36, v41
	v_mul_f32_e32 v42, v36, v42
	v_mul_f32_e32 v43, v36, v43
	v_mul_f32_e32 v44, v36, v44
	v_mul_f32_e32 v45, v36, v45
	v_mul_f32_e32 v46, v36, v46
	v_mul_f32_e32 v47, v36, v47
	v_mul_f32_e32 v40, v8, v40
	v_mul_f32_e32 v41, v9, v41
	v_mul_f32_e32 v42, v10, v42
	v_mul_f32_e32 v43, v11, v43
	v_mul_f32_e32 v44, v12, v44
	v_mul_f32_e32 v45, v13, v45
	v_mul_f32_e32 v46, v14, v46
	v_mul_f32_e32 v47, v15, v47
	global_store_dwordx4 v6, v[40:43], s[8:9] nt
	global_store_dwordx4 v6, v[44:47], s[8:9] offset:16 nt
	s_add_u32 s8, s8, 0x400000
	s_addc_u32 s9, s9, 0
	v_add_f32_e32 v56, v56, v57
	v_add_f32_e32 v58, v58, v59
	v_add_f32_e32 v60, v60, v61
	v_add_f32_e32 v62, v62, v63
	v_add_f32_e32 v64, v64, v65
	v_add_f32_e32 v66, v66, v67
	v_add_f32_e32 v68, v68, v69
	v_add_f32_e32 v70, v70, v71
	v_add_f32_e32 v56, v56, v58
	v_add_f32_e32 v60, v60, v62
	v_add_f32_e32 v64, v64, v66
	v_add_f32_e32 v68, v68, v70
	v_add_f32_e32 v56, v56, v60
	v_add_f32_e32 v64, v64, v68
	v_add_f32_e32 v56, v56, v64
	v_fmamk_f32 v56, v56, 0x3a800000, v7
	v_rsq_f32_e32 v56, v56
	v_lshlrev_b32_e32 v60, 16, v72
	v_and_b32_e32 v61, 0xffff0000, v72
	v_lshlrev_b32_e32 v62, 16, v73
	v_and_b32_e32 v63, 0xffff0000, v73
	v_lshlrev_b32_e32 v64, 16, v74
	v_and_b32_e32 v65, 0xffff0000, v74
	v_lshlrev_b32_e32 v66, 16, v75
	v_and_b32_e32 v67, 0xffff0000, v75
	s_nop 0
	v_mul_f32_e32 v60, v56, v60
	v_mul_f32_e32 v61, v56, v61
	v_mul_f32_e32 v62, v56, v62
	v_mul_f32_e32 v63, v56, v63
	v_mul_f32_e32 v64, v56, v64
	v_mul_f32_e32 v65, v56, v65
	v_mul_f32_e32 v66, v56, v66
	v_mul_f32_e32 v67, v56, v67
	v_mul_f32_e32 v60, v8, v60
	v_mul_f32_e32 v61, v9, v61
	v_mul_f32_e32 v62, v10, v62
; __device__ __forceinline__ float bflo(unsigned w) { return __uint_as_float(w << 16); }
; __device__ __forceinline__ float bfhi(unsigned w) { return __uint_as_float(w & 0xffff0000u); }
; __device__ __forceinline__ float rstd_row(const float* ss, int row) { const f32x4* p = (const f32x4*)(ss + (size_t)row * 16); const f32x4 a = p[0], b = p[1], c = p[2], d = p[3];
;     const float s = (((a[0] + a[1]) + (a[2] + a[3])) + ((b[0] + b[1]) + (b[2] + b[3]))) + (((c[0] + c[1]) + (c[2] + c[3])) + ((d[0] + d[1]) + (d[2] + d[3]))); return __builtin_amdgcn_rsqf(s * (1.f / 1024.f) + EPS); }
; __device__ __forceinline__ void final_norm_phase(const Frame& F, const bf16* h, const float* ssq, const float* gain, float* out) {
;     for (int it = F.bx * NTHR + F.tid; it < M * 128; it += F.G * NTHR) { const int row = it >> 7, c8 = (it & 127) * 8; const float rs = rstd_row(ssq, row);
;         const v4u w = *(const v4u*)(h + (size_t)row * DM_ + c8); const f32x4 g0 = *(const f32x4*)(gain + c8), g1 = *(const f32x4*)(gain + c8 + 4);
;         float* o = out + (size_t)row * DM_ + c8;
;         __builtin_nontemporal_store((f32x4){bflo(w.x) * rs * g0[0], bfhi(w.x) * rs * g0[1], bflo(w.y) * rs * g0[2], bfhi(w.y) * rs * g0[3]}, (f32x4*)o);
;         __builtin_nontemporal_store((f32x4){bflo(w.z) * rs * g1[0], bfhi(w.z) * rs * g1[1], bflo(w.w) * rs * g1[2], bfhi(w.w) * rs * g1[3]}, (f32x4*)(o + 4)); }
; }
	v_mul_f32_e32 v63, v11, v63
	v_mul_f32_e32 v64, v12, v64
	v_mul_f32_e32 v65, v13, v65
	v_mul_f32_e32 v66, v14, v66
	v_mul_f32_e32 v67, v15, v67
	global_store_dwordx4 v6, v[60:63], s[8:9] nt
	global_store_dwordx4 v6, v[64:67], s[8:9] offset:16 nt
	s_add_u32 s8, s8, 0x400000
	s_addc_u32 s9, s9, 0
	v_add_f32_e32 v76, v76, v77
	v_add_f32_e32 v78, v78, v79
	v_add_f32_e32 v80, v80, v81
	v_add_f32_e32 v82, v82, v83
	v_add_f32_e32 v84, v84, v85
	v_add_f32_e32 v86, v86, v87
	v_add_f32_e32 v88, v88, v89
	v_add_f32_e32 v90, v90, v91
	v_add_f32_e32 v76, v76, v78
	v_add_f32_e32 v80, v80, v82
	v_add_f32_e32 v84, v84, v86
	v_add_f32_e32 v88, v88, v90
	v_add_f32_e32 v76, v76, v80
	v_add_f32_e32 v84, v84, v88
	v_add_f32_e32 v76, v76, v84
	v_fmamk_f32 v76, v76, 0x3a800000, v7
	v_rsq_f32_e32 v76, v76
	v_lshlrev_b32_e32 v80, 16, v92
	v_and_b32_e32 v81, 0xffff0000, v92
	v_lshlrev_b32_e32 v82, 16, v93
	v_and_b32_e32 v83, 0xffff0000, v93
	v_lshlrev_b32_e32 v84, 16, v94
	v_and_b32_e32 v85, 0xffff0000, v94
	v_lshlrev_b32_e32 v86, 16, v95
	v_and_b32_e32 v87, 0xffff0000, v95
	s_nop 0
	v_mul_f32_e32 v80, v76, v80
	v_mul_f32_e32 v81, v76, v81
	v_mul_f32_e32 v82, v76, v82
	v_mul_f32_e32 v83, v76, v83
	v_mul_f32_e32 v84, v76, v84
	v_mul_f32_e32 v85, v76, v85
	v_mul_f32_e32 v86, v76, v86
	v_mul_f32_e32 v87, v76, v87
	v_mul_f32_e32 v80, v8, v80
	v_mul_f32_e32 v81, v9, v81
	v_mul_f32_e32 v82, v10, v82
	v_mul_f32_e32 v83, v11, v83
	v_mul_f32_e32 v84, v12, v84
	v_mul_f32_e32 v85, v13, v85
	v_mul_f32_e32 v86, v14, v86
	v_mul_f32_e32 v87, v15, v87
	global_store_dwordx4 v6, v[80:83], s[8:9] nt
	global_store_dwordx4 v6, v[84:87], s[8:9] offset:16 nt
	s_add_u32 s8, s8, 0x400000
	s_addc_u32 s9, s9, 0
	global_load_dwordx4 v[16:19], v5, s[6:7]
	global_load_dwordx4 v[20:23], v5, s[6:7] offset:16
	global_load_dwordx4 v[24:27], v5, s[6:7] offset:32
	global_load_dwordx4 v[28:31], v5, s[6:7] offset:48
	global_load_dwordx4 v[32:35], v4, s[4:5]
	s_add_u32 s4, s4, 0x200000
	s_addc_u32 s5, s5, 0
	s_add_u32 s6, s6, 0x10000
	s_addc_u32 s7, s7, 0
	global_load_dwordx4 v[36:39], v5, s[6:7]
	global_load_dwordx4 v[40:43], v5, s[6:7] offset:16
	global_load_dwordx4 v[44:47], v5, s[6:7] offset:32
	global_load_dwordx4 v[48:51], v5, s[6:7] offset:48
	global_load_dwordx4 v[52:55], v4, s[4:5]
	s_add_u32 s4, s4, 0x200000
	s_addc_u32 s5, s5, 0
	s_add_u32 s6, s6, 0x10000
	s_addc_u32 s7, s7, 0
	global_load_dwordx4 v[56:59], v5, s[6:7]
	global_load_dwordx4 v[60:63], v5, s[6:7] offset:16
	global_load_dwordx4 v[64:67], v5, s[6:7] offset:32
	global_load_dwordx4 v[68:71], v5, s[6:7] offset:48
	global_load_dwordx4 v[72:75], v4, s[4:5]
	s_add_u32 s4, s4, 0x200000
	s_addc_u32 s5, s5, 0
	s_add_u32 s6, s6, 0x10000
	s_addc_u32 s7, s7, 0
	global_load_dwordx4 v[76:79], v5, s[6:7]
	global_load_dwordx4 v[80:83], v5, s[6:7] offset:16
	global_load_dwordx4 v[84:87], v5, s[6:7] offset:32
	global_load_dwordx4 v[88:91], v5, s[6:7] offset:48
	global_load_dwordx4 v[92:95], v4, s[4:5]
	s_add_u32 s4, s4, 0x200000
	s_addc_u32 s5, s5, 0
	s_add_u32 s6, s6, 0x10000
	s_addc_u32 s7, s7, 0
	s_waitcnt vmcnt(28)
	v_add_f32_e32 v96, v96, v97
	v_add_f32_e32 v98, v98, v99
	v_add_f32_e32 v100, v100, v101
	v_add_f32_e32 v102, v102, v103
	v_add_f32_e32 v104, v104, v105
	v_add_f32_e32 v106, v106, v107
	v_add_f32_e32 v108, v108, v109
	v_add_f32_e32 v110, v110, v111
	v_add_f32_e32 v96, v96, v98
	v_add_f32_e32 v100, v100, v102
	v_add_f32_e32 v104, v104, v106
	v_add_f32_e32 v108, v108, v110
	v_add_f32_e32 v96, v96, v100
	v_add_f32_e32 v104, v104, v108
	v_add_f32_e32 v96, v96, v104
	v_fmamk_f32 v96, v96, 0x3a800000, v7
	v_rsq_f32_e32 v96, v96
	v_lshlrev_b32_e32 v100, 16, v112
	v_and_b32_e32 v101, 0xffff0000, v112
	v_lshlrev_b32_e32 v102, 16, v113
	v_and_b32_e32 v103, 0xffff0000, v113
	v_lshlrev_b32_e32 v104, 16, v114
	v_and_b32_e32 v105, 0xffff0000, v114
	v_lshlrev_b32_e32 v106, 16, v115
	v_and_b32_e32 v107, 0xffff0000, v115
	s_nop 0
	v_mul_f32_e32 v100, v96, v100
	v_mul_f32_e32 v101, v96, v101
	v_mul_f32_e32 v102, v96, v102
	v_mul_f32_e32 v103, v96, v103
	v_mul_f32_e32 v104, v96, v104
	v_mul_f32_e32 v105, v96, v105
	v_mul_f32_e32 v106, v96, v106
	v_mul_f32_e32 v107, v96, v107
	v_mul_f32_e32 v100, v8, v100
	v_mul_f32_e32 v101, v9, v101
	v_mul_f32_e32 v102, v10, v102
	v_mul_f32_e32 v103, v11, v103
	v_mul_f32_e32 v104, v12, v104
	v_mul_f32_e32 v105, v13, v105
	v_mul_f32_e32 v106, v14, v106
	v_mul_f32_e32 v107, v15, v107
	global_store_dwordx4 v6, v[100:103], s[8:9] nt
	global_store_dwordx4 v6, v[104:107], s[8:9] offset:16 nt
	s_add_u32 s8, s8, 0x400000
	s_addc_u32 s9, s9, 0
	v_add_f32_e32 v116, v116, v117
	v_add_f32_e32 v118, v118, v119
	v_add_f32_e32 v120, v120, v121
	v_add_f32_e32 v122, v122, v123
	v_add_f32_e32 v124, v124, v125
	v_add_f32_e32 v126, v126, v127
	v_add_f32_e32 v128, v128, v129
	v_add_f32_e32 v130, v130, v131
	v_add_f32_e32 v116, v116, v118
	v_add_f32_e32 v120, v120, v122
	v_add_f32_e32 v124, v124, v126
	v_add_f32_e32 v128, v128, v130
	v_add_f32_e32 v116, v116, v120
	v_add_f32_e32 v124, v124, v128
	v_add_f32_e32 v116, v116, v124
	v_fmamk_f32 v116, v116, 0x3a800000, v7
	v_rsq_f32_e32 v116, v116
	v_lshlrev_b32_e32 v120, 16, v132
	v_and_b32_e32 v121, 0xffff0000, v132
	v_lshlrev_b32_e32 v122, 16, v133
	v_and_b32_e32 v123, 0xffff0000, v133
	v_lshlrev_b32_e32 v124, 16, v134
	v_and_b32_e32 v125, 0xffff0000, v134
	v_lshlrev_b32_e32 v126, 16, v135
	v_and_b32_e32 v127, 0xffff0000, v135
	s_nop 0
	v_mul_f32_e32 v120, v116, v120
	v_mul_f32_e32 v121, v116, v121
	v_mul_f32_e32 v122, v116, v122
	v_mul_f32_e32 v123, v116, v123
	v_mul_f32_e32 v124, v116, v124
	v_mul_f32_e32 v125, v116, v125
	v_mul_f32_e32 v126, v116, v126
	v_mul_f32_e32 v127, v116, v127
; __device__ __forceinline__ float bflo(unsigned w) { return __uint_as_float(w << 16); }
; __device__ __forceinline__ float bfhi(unsigned w) { return __uint_as_float(w & 0xffff0000u); }
; __device__ __forceinline__ float rstd_row(const float* ss, int row) { const f32x4* p = (const f32x4*)(ss + (size_t)row * 16); const f32x4 a = p[0], b = p[1], c = p[2], d = p[3];
;     const float s = (((a[0] + a[1]) + (a[2] + a[3])) + ((b[0] + b[1]) + (b[2] + b[3]))) + (((c[0] + c[1]) + (c[2] + c[3])) + ((d[0] + d[1]) + (d[2] + d[3]))); return __builtin_amdgcn_rsqf(s * (1.f / 1024.f) + EPS); }
; __device__ __forceinline__ void final_norm_phase(const Frame& F, const bf16* h, const float* ssq, const float* gain, float* out) {
;     for (int it = F.bx * NTHR + F.tid; it < M * 128; it += F.G * NTHR) { const int row = it >> 7, c8 = (it & 127) * 8; const float rs = rstd_row(ssq, row);
;         const v4u w = *(const v4u*)(h + (size_t)row * DM_ + c8); const f32x4 g0 = *(const f32x4*)(gain + c8), g1 = *(const f32x4*)(gain + c8 + 4);
;         float* o = out + (size_t)row * DM_ + c8;
;         __builtin_nontemporal_store((f32x4){bflo(w.x) * rs * g0[0], bfhi(w.x) * rs * g0[1], bflo(w.y) * rs * g0[2], bfhi(w.y) * rs * g0[3]}, (f32x4*)o);
;         __builtin_nontemporal_store((f32x4){bflo(w.z) * rs * g1[0], bfhi(w.z) * rs * g1[1], bflo(w.w) * rs * g1[2], bfhi(w.w) * rs * g1[3]}, (f32x4*)(o + 4)); }
	v_mul_f32_e32 v120, v8, v120
	v_mul_f32_e32 v121, v9, v121
	v_mul_f32_e32 v122, v10, v122
	v_mul_f32_e32 v123, v11, v123
	v_mul_f32_e32 v124, v12, v124
	v_mul_f32_e32 v125, v13, v125
	v_mul_f32_e32 v126, v14, v126
	v_mul_f32_e32 v127, v15, v127
	global_store_dwordx4 v6, v[120:123], s[8:9] nt
	global_store_dwordx4 v6, v[124:127], s[8:9] offset:16 nt
	s_add_u32 s8, s8, 0x400000
	s_addc_u32 s9, s9, 0
	v_add_f32_e32 v136, v136, v137
	v_add_f32_e32 v138, v138, v139
	v_add_f32_e32 v140, v140, v141
	v_add_f32_e32 v142, v142, v143
	v_add_f32_e32 v144, v144, v145
	v_add_f32_e32 v146, v146, v147
	v_add_f32_e32 v148, v148, v149
	v_add_f32_e32 v150, v150, v151
	v_add_f32_e32 v136, v136, v138
	v_add_f32_e32 v140, v140, v142
	v_add_f32_e32 v144, v144, v146
	v_add_f32_e32 v148, v148, v150
	v_add_f32_e32 v136, v136, v140
	v_add_f32_e32 v144, v144, v148
	v_add_f32_e32 v136, v136, v144
	v_fmamk_f32 v136, v136, 0x3a800000, v7
	v_rsq_f32_e32 v136, v136
	v_lshlrev_b32_e32 v140, 16, v152
	v_and_b32_e32 v141, 0xffff0000, v152
	v_lshlrev_b32_e32 v142, 16, v153
	v_and_b32_e32 v143, 0xffff0000, v153
	v_lshlrev_b32_e32 v144, 16, v154
	v_and_b32_e32 v145, 0xffff0000, v154
	v_lshlrev_b32_e32 v146, 16, v155
	v_and_b32_e32 v147, 0xffff0000, v155
	s_nop 0
	v_mul_f32_e32 v140, v136, v140
	v_mul_f32_e32 v141, v136, v141
	v_mul_f32_e32 v142, v136, v142
	v_mul_f32_e32 v143, v136, v143
	v_mul_f32_e32 v144, v136, v144
	v_mul_f32_e32 v145, v136, v145
	v_mul_f32_e32 v146, v136, v146
	v_mul_f32_e32 v147, v136, v147
	v_mul_f32_e32 v140, v8, v140
	v_mul_f32_e32 v141, v9, v141
	v_mul_f32_e32 v142, v10, v142
	v_mul_f32_e32 v143, v11, v143
	v_mul_f32_e32 v144, v12, v144
	v_mul_f32_e32 v145, v13, v145
	v_mul_f32_e32 v146, v14, v146
	v_mul_f32_e32 v147, v15, v147
	global_store_dwordx4 v6, v[140:143], s[8:9] nt
	global_store_dwordx4 v6, v[144:147], s[8:9] offset:16 nt
	s_add_u32 s8, s8, 0x400000
	s_addc_u32 s9, s9, 0
	v_add_f32_e32 v156, v156, v157
	v_add_f32_e32 v158, v158, v159
	v_add_f32_e32 v160, v160, v161
	v_add_f32_e32 v162, v162, v163
	v_add_f32_e32 v164, v164, v165
	v_add_f32_e32 v166, v166, v167
	v_add_f32_e32 v168, v168, v169
	v_add_f32_e32 v170, v170, v171
	v_add_f32_e32 v156, v156, v158
	v_add_f32_e32 v160, v160, v162
	v_add_f32_e32 v164, v164, v166
	v_add_f32_e32 v168, v168, v170
	v_add_f32_e32 v156, v156, v160
	v_add_f32_e32 v164, v164, v168
	v_add_f32_e32 v156, v156, v164
	v_fmamk_f32 v156, v156, 0x3a800000, v7
	v_rsq_f32_e32 v156, v156
	v_lshlrev_b32_e32 v160, 16, v172
	v_and_b32_e32 v161, 0xffff0000, v172
	v_lshlrev_b32_e32 v162, 16, v173
	v_and_b32_e32 v163, 0xffff0000, v173
	v_lshlrev_b32_e32 v164, 16, v174
	v_and_b32_e32 v165, 0xffff0000, v174
	v_lshlrev_b32_e32 v166, 16, v175
	v_and_b32_e32 v167, 0xffff0000, v175
	s_nop 0
	v_mul_f32_e32 v160, v156, v160
	v_mul_f32_e32 v161, v156, v161
	v_mul_f32_e32 v162, v156, v162
	v_mul_f32_e32 v163, v156, v163
	v_mul_f32_e32 v164, v156, v164
	v_mul_f32_e32 v165, v156, v165
	v_mul_f32_e32 v166, v156, v166
	v_mul_f32_e32 v167, v156, v167
	v_mul_f32_e32 v160, v8, v160
	v_mul_f32_e32 v161, v9, v161
	v_mul_f32_e32 v162, v10, v162
	v_mul_f32_e32 v163, v11, v163
	v_mul_f32_e32 v164, v12, v164
	v_mul_f32_e32 v165, v13, v165
	v_mul_f32_e32 v166, v14, v166
	v_mul_f32_e32 v167, v15, v167
	global_store_dwordx4 v6, v[160:163], s[8:9] nt
	global_store_dwordx4 v6, v[164:167], s[8:9] offset:16 nt
	s_add_u32 s8, s8, 0x400000
	s_addc_u32 s9, s9, 0
	global_load_dwordx4 v[96:99], v5, s[6:7]
	global_load_dwordx4 v[100:103], v5, s[6:7] offset:16
	global_load_dwordx4 v[104:107], v5, s[6:7] offset:32
	global_load_dwordx4 v[108:111], v5, s[6:7] offset:48
	global_load_dwordx4 v[112:115], v4, s[4:5]
	s_add_u32 s4, s4, 0x200000
	s_addc_u32 s5, s5, 0
	s_add_u32 s6, s6, 0x10000
	s_addc_u32 s7, s7, 0
	global_load_dwordx4 v[116:119], v5, s[6:7]
	global_load_dwordx4 v[120:123], v5, s[6:7] offset:16
	global_load_dwordx4 v[124:127], v5, s[6:7] offset:32
	global_load_dwordx4 v[128:131], v5, s[6:7] offset:48
	global_load_dwordx4 v[132:135], v4, s[4:5]
	s_add_u32 s4, s4, 0x200000
	s_addc_u32 s5, s5, 0
	s_add_u32 s6, s6, 0x10000
	s_addc_u32 s7, s7, 0
	global_load_dwordx4 v[136:139], v5, s[6:7]
	global_load_dwordx4 v[140:143], v5, s[6:7] offset:16
	global_load_dwordx4 v[144:147], v5, s[6:7] offset:32
	global_load_dwordx4 v[148:151], v5, s[6:7] offset:48
	global_load_dwordx4 v[152:155], v4, s[4:5]
	s_add_u32 s4, s4, 0x200000
	s_addc_u32 s5, s5, 0
	s_add_u32 s6, s6, 0x10000
	s_addc_u32 s7, s7, 0
	global_load_dwordx4 v[156:159], v5, s[6:7]
	global_load_dwordx4 v[160:163], v5, s[6:7] offset:16
	global_load_dwordx4 v[164:167], v5, s[6:7] offset:32
	global_load_dwordx4 v[168:171], v5, s[6:7] offset:48
	global_load_dwordx4 v[172:175], v4, s[4:5]
	s_add_u32 s4, s4, 0x200000
	s_addc_u32 s5, s5, 0
	s_add_u32 s6, s6, 0x10000
	s_addc_u32 s7, s7, 0
	s_waitcnt vmcnt(28)
; __device__ __forceinline__ float bflo(unsigned w) { return __uint_as_float(w << 16); }
; __device__ __forceinline__ float bfhi(unsigned w) { return __uint_as_float(w & 0xffff0000u); }
; __device__ __forceinline__ float rstd_row(const float* ss, int row) { const f32x4* p = (const f32x4*)(ss + (size_t)row * 16); const f32x4 a = p[0], b = p[1], c = p[2], d = p[3];
;     const float s = (((a[0] + a[1]) + (a[2] + a[3])) + ((b[0] + b[1]) + (b[2] + b[3]))) + (((c[0] + c[1]) + (c[2] + c[3])) + ((d[0] + d[1]) + (d[2] + d[3]))); return __builtin_amdgcn_rsqf(s * (1.f / 1024.f) + EPS); }
; __device__ __forceinline__ void final_norm_phase(const Frame& F, const bf16* h, const float* ssq, const float* gain, float* out) {
;     for (int it = F.bx * NTHR + F.tid; it < M * 128; it += F.G * NTHR) { const int row = it >> 7, c8 = (it & 127) * 8; const float rs = rstd_row(ssq, row);
;         const v4u w = *(const v4u*)(h + (size_t)row * DM_ + c8); const f32x4 g0 = *(const f32x4*)(gain + c8), g1 = *(const f32x4*)(gain + c8 + 4);
;         float* o = out + (size_t)row * DM_ + c8;
;         __builtin_nontemporal_store((f32x4){bflo(w.x) * rs * g0[0], bfhi(w.x) * rs * g0[1], bflo(w.y) * rs * g0[2], bfhi(w.y) * rs * g0[3]}, (f32x4*)o);
;         __builtin_nontemporal_store((f32x4){bflo(w.z) * rs * g1[0], bfhi(w.z) * rs * g1[1], bflo(w.w) * rs * g1[2], bfhi(w.w) * rs * g1[3]}, (f32x4*)(o + 4)); }
	v_add_f32_e32 v16, v16, v17
	v_add_f32_e32 v18, v18, v19
	v_add_f32_e32 v20, v20, v21
	v_add_f32_e32 v22, v22, v23
	v_add_f32_e32 v24, v24, v25
	v_add_f32_e32 v26, v26, v27
	v_add_f32_e32 v28, v28, v29
	v_add_f32_e32 v30, v30, v31
	v_add_f32_e32 v16, v16, v18
	v_add_f32_e32 v20, v20, v22
	v_add_f32_e32 v24, v24, v26
	v_add_f32_e32 v28, v28, v30
	v_add_f32_e32 v16, v16, v20
	v_add_f32_e32 v24, v24, v28
	v_add_f32_e32 v16, v16, v24
	v_fmamk_f32 v16, v16, 0x3a800000, v7
	v_rsq_f32_e32 v16, v16
	v_lshlrev_b32_e32 v20, 16, v32
	v_and_b32_e32 v21, 0xffff0000, v32
	v_lshlrev_b32_e32 v22, 16, v33
	v_and_b32_e32 v23, 0xffff0000, v33
	v_lshlrev_b32_e32 v24, 16, v34
	v_and_b32_e32 v25, 0xffff0000, v34
	v_lshlrev_b32_e32 v26, 16, v35
	v_and_b32_e32 v27, 0xffff0000, v35
	s_nop 0
	v_mul_f32_e32 v20, v16, v20
	v_mul_f32_e32 v21, v16, v21
	v_mul_f32_e32 v22, v16, v22
	v_mul_f32_e32 v23, v16, v23
	v_mul_f32_e32 v24, v16, v24
	v_mul_f32_e32 v25, v16, v25
	v_mul_f32_e32 v26, v16, v26
	v_mul_f32_e32 v27, v16, v27
	v_mul_f32_e32 v20, v8, v20
	v_mul_f32_e32 v21, v9, v21
	v_mul_f32_e32 v22, v10, v22
	v_mul_f32_e32 v23, v11, v23
	v_mul_f32_e32 v24, v12, v24
	v_mul_f32_e32 v25, v13, v25
	v_mul_f32_e32 v26, v14, v26
	v_mul_f32_e32 v27, v15, v27
	global_store_dwordx4 v6, v[20:23], s[8:9] nt
	global_store_dwordx4 v6, v[24:27], s[8:9] offset:16 nt
	s_add_u32 s8, s8, 0x400000
	s_addc_u32 s9, s9, 0
	v_add_f32_e32 v36, v36, v37
	v_add_f32_e32 v38, v38, v39
	v_add_f32_e32 v40, v40, v41
	v_add_f32_e32 v42, v42, v43
	v_add_f32_e32 v44, v44, v45
	v_add_f32_e32 v46, v46, v47
	v_add_f32_e32 v48, v48, v49
	v_add_f32_e32 v50, v50, v51
	v_add_f32_e32 v36, v36, v38
	v_add_f32_e32 v40, v40, v42
	v_add_f32_e32 v44, v44, v46
	v_add_f32_e32 v48, v48, v50
	v_add_f32_e32 v36, v36, v40
	v_add_f32_e32 v44, v44, v48
	v_add_f32_e32 v36, v36, v44
	v_fmamk_f32 v36, v36, 0x3a800000, v7
	v_rsq_f32_e32 v36, v36
	v_lshlrev_b32_e32 v40, 16, v52
	v_and_b32_e32 v41, 0xffff0000, v52
	v_lshlrev_b32_e32 v42, 16, v53
	v_and_b32_e32 v43, 0xffff0000, v53
	v_lshlrev_b32_e32 v44, 16, v54
	v_and_b32_e32 v45, 0xffff0000, v54
	v_lshlrev_b32_e32 v46, 16, v55
	v_and_b32_e32 v47, 0xffff0000, v55
	s_nop 0
	v_mul_f32_e32 v40, v36, v40
	v_mul_f32_e32 v41, v36, v41
	v_mul_f32_e32 v42, v36, v42
	v_mul_f32_e32 v43, v36, v43
	v_mul_f32_e32 v44, v36, v44
	v_mul_f32_e32 v45, v36, v45
	v_mul_f32_e32 v46, v36, v46
	v_mul_f32_e32 v47, v36, v47
	v_mul_f32_e32 v40, v8, v40
	v_mul_f32_e32 v41, v9, v41
	v_mul_f32_e32 v42, v10, v42
	v_mul_f32_e32 v43, v11, v43
	v_mul_f32_e32 v44, v12, v44
	v_mul_f32_e32 v45, v13, v45
	v_mul_f32_e32 v46, v14, v46
	v_mul_f32_e32 v47, v15, v47
	global_store_dwordx4 v6, v[40:43], s[8:9] nt
	global_store_dwordx4 v6, v[44:47], s[8:9] offset:16 nt
	s_add_u32 s8, s8, 0x400000
	s_addc_u32 s9, s9, 0
	v_add_f32_e32 v56, v56, v57
	v_add_f32_e32 v58, v58, v59
	v_add_f32_e32 v60, v60, v61
	v_add_f32_e32 v62, v62, v63
	v_add_f32_e32 v64, v64, v65
	v_add_f32_e32 v66, v66, v67
	v_add_f32_e32 v68, v68, v69
	v_add_f32_e32 v70, v70, v71
	v_add_f32_e32 v56, v56, v58
	v_add_f32_e32 v60, v60, v62
	v_add_f32_e32 v64, v64, v66
	v_add_f32_e32 v68, v68, v70
	v_add_f32_e32 v56, v56, v60
	v_add_f32_e32 v64, v64, v68
	v_add_f32_e32 v56, v56, v64
	v_fmamk_f32 v56, v56, 0x3a800000, v7
	v_rsq_f32_e32 v56, v56
	v_lshlrev_b32_e32 v60, 16, v72
	v_and_b32_e32 v61, 0xffff0000, v72
	v_lshlrev_b32_e32 v62, 16, v73
	v_and_b32_e32 v63, 0xffff0000, v73
	v_lshlrev_b32_e32 v64, 16, v74
	v_and_b32_e32 v65, 0xffff0000, v74
	v_lshlrev_b32_e32 v66, 16, v75
	v_and_b32_e32 v67, 0xffff0000, v75
	s_nop 0
	v_mul_f32_e32 v60, v56, v60
	v_mul_f32_e32 v61, v56, v61
	v_mul_f32_e32 v62, v56, v62
	v_mul_f32_e32 v63, v56, v63
	v_mul_f32_e32 v64, v56, v64
	v_mul_f32_e32 v65, v56, v65
	v_mul_f32_e32 v66, v56, v66
	v_mul_f32_e32 v67, v56, v67
	v_mul_f32_e32 v60, v8, v60
	v_mul_f32_e32 v61, v9, v61
	v_mul_f32_e32 v62, v10, v62
	v_mul_f32_e32 v63, v11, v63
	v_mul_f32_e32 v64, v12, v64
	v_mul_f32_e32 v65, v13, v65
	v_mul_f32_e32 v66, v14, v66
	v_mul_f32_e32 v67, v15, v67
	global_store_dwordx4 v6, v[60:63], s[8:9] nt
	global_store_dwordx4 v6, v[64:67], s[8:9] offset:16 nt
	s_add_u32 s8, s8, 0x400000
	s_addc_u32 s9, s9, 0
	v_add_f32_e32 v76, v76, v77
	v_add_f32_e32 v78, v78, v79
	v_add_f32_e32 v80, v80, v81
	v_add_f32_e32 v82, v82, v83
	v_add_f32_e32 v84, v84, v85
	v_add_f32_e32 v86, v86, v87
	v_add_f32_e32 v88, v88, v89
	v_add_f32_e32 v90, v90, v91
	v_add_f32_e32 v76, v76, v78
	v_add_f32_e32 v80, v80, v82
	v_add_f32_e32 v84, v84, v86
	v_add_f32_e32 v88, v88, v90
	v_add_f32_e32 v76, v76, v80
	v_add_f32_e32 v84, v84, v88
	v_add_f32_e32 v76, v76, v84
	v_fmamk_f32 v76, v76, 0x3a800000, v7
	v_rsq_f32_e32 v76, v76
	v_lshlrev_b32_e32 v80, 16, v92
	v_and_b32_e32 v81, 0xffff0000, v92
	v_lshlrev_b32_e32 v82, 16, v93
	v_and_b32_e32 v83, 0xffff0000, v93
	v_lshlrev_b32_e32 v84, 16, v94
	v_and_b32_e32 v85, 0xffff0000, v94
	v_lshlrev_b32_e32 v86, 16, v95
	v_and_b32_e32 v87, 0xffff0000, v95
	s_nop 0
	v_mul_f32_e32 v80, v76, v80
	v_mul_f32_e32 v81, v76, v81
	v_mul_f32_e32 v82, v76, v82
	v_mul_f32_e32 v83, v76, v83
	v_mul_f32_e32 v84, v76, v84
	v_mul_f32_e32 v85, v76, v85
	v_mul_f32_e32 v86, v76, v86
	v_mul_f32_e32 v87, v76, v87
	v_mul_f32_e32 v80, v8, v80
	v_mul_f32_e32 v81, v9, v81
	v_mul_f32_e32 v82, v10, v82
	v_mul_f32_e32 v83, v11, v83
	v_mul_f32_e32 v84, v12, v84
	v_mul_f32_e32 v85, v13, v85
	v_mul_f32_e32 v86, v14, v86
	v_mul_f32_e32 v87, v15, v87
	global_store_dwordx4 v6, v[80:83], s[8:9] nt
	global_store_dwordx4 v6, v[84:87], s[8:9] offset:16 nt
	s_add_u32 s8, s8, 0x400000
	s_addc_u32 s9, s9, 0
	global_load_dwordx4 v[16:19], v5, s[6:7]
	global_load_dwordx4 v[20:23], v5, s[6:7] offset:16
	global_load_dwordx4 v[24:27], v5, s[6:7] offset:32
	global_load_dwordx4 v[28:31], v5, s[6:7] offset:48
	global_load_dwordx4 v[32:35], v4, s[4:5]
	s_add_u32 s4, s4, 0x200000
	s_addc_u32 s5, s5, 0
	s_add_u32 s6, s6, 0x10000
	s_addc_u32 s7, s7, 0
	global_load_dwordx4 v[36:39], v5, s[6:7]
	global_load_dwordx4 v[40:43], v5, s[6:7] offset:16
	global_load_dwordx4 v[44:47], v5, s[6:7] offset:32
	global_load_dwordx4 v[48:51], v5, s[6:7] offset:48
	global_load_dwordx4 v[52:55], v4, s[4:5]
	s_add_u32 s4, s4, 0x200000
	s_addc_u32 s5, s5, 0
	s_add_u32 s6, s6, 0x10000
	s_addc_u32 s7, s7, 0
	global_load_dwordx4 v[56:59], v5, s[6:7]
	global_load_dwordx4 v[60:63], v5, s[6:7] offset:16
	global_load_dwordx4 v[64:67], v5, s[6:7] offset:32
	global_load_dwordx4 v[68:71], v5, s[6:7] offset:48
	global_load_dwordx4 v[72:75], v4, s[4:5]
	s_add_u32 s4, s4, 0x200000
	s_addc_u32 s5, s5, 0
	s_add_u32 s6, s6, 0x10000
	s_addc_u32 s7, s7, 0
	global_load_dwordx4 v[76:79], v5, s[6:7]
	global_load_dwordx4 v[80:83], v5, s[6:7] offset:16
	global_load_dwordx4 v[84:87], v5, s[6:7] offset:32
	global_load_dwordx4 v[88:91], v5, s[6:7] offset:48
	global_load_dwordx4 v[92:95], v4, s[4:5]
	s_add_u32 s4, s4, 0x200000
	s_addc_u32 s5, s5, 0
	s_add_u32 s6, s6, 0x10000
	s_addc_u32 s7, s7, 0
	s_waitcnt vmcnt(28)
; __device__ __forceinline__ float bflo(unsigned w) { return __uint_as_float(w << 16); }
; __device__ __forceinline__ float bfhi(unsigned w) { return __uint_as_float(w & 0xffff0000u); }
; __device__ __forceinline__ float rstd_row(const float* ss, int row) { const f32x4* p = (const f32x4*)(ss + (size_t)row * 16); const f32x4 a = p[0], b = p[1], c = p[2], d = p[3];
;     const float s = (((a[0] + a[1]) + (a[2] + a[3])) + ((b[0] + b[1]) + (b[2] + b[3]))) + (((c[0] + c[1]) + (c[2] + c[3])) + ((d[0] + d[1]) + (d[2] + d[3]))); return __builtin_amdgcn_rsqf(s * (1.f / 1024.f) + EPS); }
; __device__ __forceinline__ void final_norm_phase(const Frame& F, const bf16* h, const float* ssq, const float* gain, float* out) {
;     for (int it = F.bx * NTHR + F.tid; it < M * 128; it += F.G * NTHR) { const int row = it >> 7, c8 = (it & 127) * 8; const float rs = rstd_row(ssq, row);
;         const v4u w = *(const v4u*)(h + (size_t)row * DM_ + c8); const f32x4 g0 = *(const f32x4*)(gain + c8), g1 = *(const f32x4*)(gain + c8 + 4);
;         float* o = out + (size_t)row * DM_ + c8;
;         __builtin_nontemporal_store((f32x4){bflo(w.x) * rs * g0[0], bfhi(w.x) * rs * g0[1], bflo(w.y) * rs * g0[2], bfhi(w.y) * rs * g0[3]}, (f32x4*)o);
;         __builtin_nontemporal_store((f32x4){bflo(w.z) * rs * g1[0], bfhi(w.z) * rs * g1[1], bflo(w.w) * rs * g1[2], bfhi(w.w) * rs * g1[3]}, (f32x4*)(o + 4)); }
	v_add_f32_e32 v96, v96, v97
	v_add_f32_e32 v98, v98, v99
	v_add_f32_e32 v100, v100, v101
	v_add_f32_e32 v102, v102, v103
	v_add_f32_e32 v104, v104, v105
	v_add_f32_e32 v106, v106, v107
	v_add_f32_e32 v108, v108, v109
	v_add_f32_e32 v110, v110, v111
	v_add_f32_e32 v96, v96, v98
	v_add_f32_e32 v100, v100, v102
	v_add_f32_e32 v104, v104, v106
	v_add_f32_e32 v108, v108, v110
	v_add_f32_e32 v96, v96, v100
	v_add_f32_e32 v104, v104, v108
	v_add_f32_e32 v96, v96, v104
	v_fmamk_f32 v96, v96, 0x3a800000, v7
	v_rsq_f32_e32 v96, v96
	v_lshlrev_b32_e32 v100, 16, v112
	v_and_b32_e32 v101, 0xffff0000, v112
	v_lshlrev_b32_e32 v102, 16, v113
	v_and_b32_e32 v103, 0xffff0000, v113
	v_lshlrev_b32_e32 v104, 16, v114
	v_and_b32_e32 v105, 0xffff0000, v114
	v_lshlrev_b32_e32 v106, 16, v115
	v_and_b32_e32 v107, 0xffff0000, v115
	s_nop 0
	v_mul_f32_e32 v100, v96, v100
	v_mul_f32_e32 v101, v96, v101
	v_mul_f32_e32 v102, v96, v102
	v_mul_f32_e32 v103, v96, v103
	v_mul_f32_e32 v104, v96, v104
	v_mul_f32_e32 v105, v96, v105
	v_mul_f32_e32 v106, v96, v106
	v_mul_f32_e32 v107, v96, v107
	v_mul_f32_e32 v100, v8, v100
	v_mul_f32_e32 v101, v9, v101
	v_mul_f32_e32 v102, v10, v102
	v_mul_f32_e32 v103, v11, v103
	v_mul_f32_e32 v104, v12, v104
	v_mul_f32_e32 v105, v13, v105
	v_mul_f32_e32 v106, v14, v106
	v_mul_f32_e32 v107, v15, v107
	global_store_dwordx4 v6, v[100:103], s[8:9] nt
	global_store_dwordx4 v6, v[104:107], s[8:9] offset:16 nt
	s_add_u32 s8, s8, 0x400000
	s_addc_u32 s9, s9, 0
	v_add_f32_e32 v116, v116, v117
	v_add_f32_e32 v118, v118, v119
	v_add_f32_e32 v120, v120, v121
	v_add_f32_e32 v122, v122, v123
	v_add_f32_e32 v124, v124, v125
	v_add_f32_e32 v126, v126, v127
	v_add_f32_e32 v128, v128, v129
	v_add_f32_e32 v130, v130, v131
	v_add_f32_e32 v116, v116, v118
	v_add_f32_e32 v120, v120, v122
	v_add_f32_e32 v124, v124, v126
	v_add_f32_e32 v128, v128, v130
	v_add_f32_e32 v116, v116, v120
	v_add_f32_e32 v124, v124, v128
	v_add_f32_e32 v116, v116, v124
	v_fmamk_f32 v116, v116, 0x3a800000, v7
	v_rsq_f32_e32 v116, v116
	v_lshlrev_b32_e32 v120, 16, v132
	v_and_b32_e32 v121, 0xffff0000, v132
	v_lshlrev_b32_e32 v122, 16, v133
	v_and_b32_e32 v123, 0xffff0000, v133
	v_lshlrev_b32_e32 v124, 16, v134
	v_and_b32_e32 v125, 0xffff0000, v134
	v_lshlrev_b32_e32 v126, 16, v135
	v_and_b32_e32 v127, 0xffff0000, v135
	s_nop 0
	v_mul_f32_e32 v120, v116, v120
	v_mul_f32_e32 v121, v116, v121
	v_mul_f32_e32 v122, v116, v122
	v_mul_f32_e32 v123, v116, v123
	v_mul_f32_e32 v124, v116, v124
	v_mul_f32_e32 v125, v116, v125
	v_mul_f32_e32 v126, v116, v126
	v_mul_f32_e32 v127, v116, v127
	v_mul_f32_e32 v120, v8, v120
	v_mul_f32_e32 v121, v9, v121
	v_mul_f32_e32 v122, v10, v122
	v_mul_f32_e32 v123, v11, v123
	v_mul_f32_e32 v124, v12, v124
	v_mul_f32_e32 v125, v13, v125
	v_mul_f32_e32 v126, v14, v126
	v_mul_f32_e32 v127, v15, v127
	global_store_dwordx4 v6, v[120:123], s[8:9] nt
	global_store_dwordx4 v6, v[124:127], s[8:9] offset:16 nt
	s_add_u32 s8, s8, 0x400000
	s_addc_u32 s9, s9, 0
	v_add_f32_e32 v136, v136, v137
	v_add_f32_e32 v138, v138, v139
	v_add_f32_e32 v140, v140, v141
	v_add_f32_e32 v142, v142, v143
	v_add_f32_e32 v144, v144, v145
	v_add_f32_e32 v146, v146, v147
	v_add_f32_e32 v148, v148, v149
	v_add_f32_e32 v150, v150, v151
	v_add_f32_e32 v136, v136, v138
	v_add_f32_e32 v140, v140, v142
	v_add_f32_e32 v144, v144, v146
	v_add_f32_e32 v148, v148, v150
	v_add_f32_e32 v136, v136, v140
	v_add_f32_e32 v144, v144, v148
	v_add_f32_e32 v136, v136, v144
	v_fmamk_f32 v136, v136, 0x3a800000, v7
	v_rsq_f32_e32 v136, v136
	v_lshlrev_b32_e32 v140, 16, v152
	v_and_b32_e32 v141, 0xffff0000, v152
	v_lshlrev_b32_e32 v142, 16, v153
	v_and_b32_e32 v143, 0xffff0000, v153
	v_lshlrev_b32_e32 v144, 16, v154
	v_and_b32_e32 v145, 0xffff0000, v154
	v_lshlrev_b32_e32 v146, 16, v155
	v_and_b32_e32 v147, 0xffff0000, v155
	s_nop 0
	v_mul_f32_e32 v140, v136, v140
	v_mul_f32_e32 v141, v136, v141
	v_mul_f32_e32 v142, v136, v142
	v_mul_f32_e32 v143, v136, v143
	v_mul_f32_e32 v144, v136, v144
	v_mul_f32_e32 v145, v136, v145
	v_mul_f32_e32 v146, v136, v146
	v_mul_f32_e32 v147, v136, v147
	v_mul_f32_e32 v140, v8, v140
	v_mul_f32_e32 v141, v9, v141
	v_mul_f32_e32 v142, v10, v142
	v_mul_f32_e32 v143, v11, v143
	v_mul_f32_e32 v144, v12, v144
	v_mul_f32_e32 v145, v13, v145
	v_mul_f32_e32 v146, v14, v146
	v_mul_f32_e32 v147, v15, v147
	global_store_dwordx4 v6, v[140:143], s[8:9] nt
	global_store_dwordx4 v6, v[144:147], s[8:9] offset:16 nt
	s_add_u32 s8, s8, 0x400000
	s_addc_u32 s9, s9, 0
	v_add_f32_e32 v156, v156, v157
	v_add_f32_e32 v158, v158, v159
	v_add_f32_e32 v160, v160, v161
	v_add_f32_e32 v162, v162, v163
	v_add_f32_e32 v164, v164, v165
	v_add_f32_e32 v166, v166, v167
	v_add_f32_e32 v168, v168, v169
	v_add_f32_e32 v170, v170, v171
	v_add_f32_e32 v156, v156, v158
	v_add_f32_e32 v160, v160, v162
	v_add_f32_e32 v164, v164, v166
	v_add_f32_e32 v168, v168, v170
	v_add_f32_e32 v156, v156, v160
	v_add_f32_e32 v164, v164, v168
	v_add_f32_e32 v156, v156, v164
	v_fmamk_f32 v156, v156, 0x3a800000, v7
	v_rsq_f32_e32 v156, v156
	v_lshlrev_b32_e32 v160, 16, v172
	v_and_b32_e32 v161, 0xffff0000, v172
	v_lshlrev_b32_e32 v162, 16, v173
	v_and_b32_e32 v163, 0xffff0000, v173
	v_lshlrev_b32_e32 v164, 16, v174
	v_and_b32_e32 v165, 0xffff0000, v174
	v_lshlrev_b32_e32 v166, 16, v175
	v_and_b32_e32 v167, 0xffff0000, v175
	s_nop 0
	v_mul_f32_e32 v160, v156, v160
	v_mul_f32_e32 v161, v156, v161
	v_mul_f32_e32 v162, v156, v162
	v_mul_f32_e32 v163, v156, v163
	v_mul_f32_e32 v164, v156, v164
	v_mul_f32_e32 v165, v156, v165
	v_mul_f32_e32 v166, v156, v166
	v_mul_f32_e32 v167, v156, v167
	v_mul_f32_e32 v160, v8, v160
	v_mul_f32_e32 v161, v9, v161
; __device__ __forceinline__ float bflo(unsigned w) { return __uint_as_float(w << 16); }
; __device__ __forceinline__ float bfhi(unsigned w) { return __uint_as_float(w & 0xffff0000u); }
; __device__ __forceinline__ float rstd_row(const float* ss, int row) { const f32x4* p = (const f32x4*)(ss + (size_t)row * 16); const f32x4 a = p[0], b = p[1], c = p[2], d = p[3];
;     const float s = (((a[0] + a[1]) + (a[2] + a[3])) + ((b[0] + b[1]) + (b[2] + b[3]))) + (((c[0] + c[1]) + (c[2] + c[3])) + ((d[0] + d[1]) + (d[2] + d[3]))); return __builtin_amdgcn_rsqf(s * (1.f / 1024.f) + EPS); }
; __device__ __forceinline__ void final_norm_phase(const Frame& F, const bf16* h, const float* ssq, const float* gain, float* out) {
;     for (int it = F.bx * NTHR + F.tid; it < M * 128; it += F.G * NTHR) { const int row = it >> 7, c8 = (it & 127) * 8; const float rs = rstd_row(ssq, row);
;         const v4u w = *(const v4u*)(h + (size_t)row * DM_ + c8); const f32x4 g0 = *(const f32x4*)(gain + c8), g1 = *(const f32x4*)(gain + c8 + 4);
;         float* o = out + (size_t)row * DM_ + c8;
;         __builtin_nontemporal_store((f32x4){bflo(w.x) * rs * g0[0], bfhi(w.x) * rs * g0[1], bflo(w.y) * rs * g0[2], bfhi(w.y) * rs * g0[3]}, (f32x4*)o);
;         __builtin_nontemporal_store((f32x4){bflo(w.z) * rs * g1[0], bfhi(w.z) * rs * g1[1], bflo(w.w) * rs * g1[2], bfhi(w.w) * rs * g1[3]}, (f32x4*)(o + 4)); }
	v_mul_f32_e32 v162, v10, v162
	v_mul_f32_e32 v163, v11, v163
	v_mul_f32_e32 v164, v12, v164
	v_mul_f32_e32 v165, v13, v165
	v_mul_f32_e32 v166, v14, v166
	v_mul_f32_e32 v167, v15, v167
	global_store_dwordx4 v6, v[160:163], s[8:9] nt
	global_store_dwordx4 v6, v[164:167], s[8:9] offset:16 nt
	s_add_u32 s8, s8, 0x400000
	s_addc_u32 s9, s9, 0
	global_load_dwordx4 v[96:99], v5, s[6:7]
	global_load_dwordx4 v[100:103], v5, s[6:7] offset:16
	global_load_dwordx4 v[104:107], v5, s[6:7] offset:32
	global_load_dwordx4 v[108:111], v5, s[6:7] offset:48
	global_load_dwordx4 v[112:115], v4, s[4:5]
	s_add_u32 s4, s4, 0x200000
	s_addc_u32 s5, s5, 0
	s_add_u32 s6, s6, 0x10000
	s_addc_u32 s7, s7, 0
	global_load_dwordx4 v[116:119], v5, s[6:7]
	global_load_dwordx4 v[120:123], v5, s[6:7] offset:16
	global_load_dwordx4 v[124:127], v5, s[6:7] offset:32
	global_load_dwordx4 v[128:131], v5, s[6:7] offset:48
	global_load_dwordx4 v[132:135], v4, s[4:5]
	s_add_u32 s4, s4, 0x200000
	s_addc_u32 s5, s5, 0
	s_add_u32 s6, s6, 0x10000
	s_addc_u32 s7, s7, 0
	global_load_dwordx4 v[136:139], v5, s[6:7]
	global_load_dwordx4 v[140:143], v5, s[6:7] offset:16
	global_load_dwordx4 v[144:147], v5, s[6:7] offset:32
	global_load_dwordx4 v[148:151], v5, s[6:7] offset:48
	global_load_dwordx4 v[152:155], v4, s[4:5]
	s_add_u32 s4, s4, 0x200000
	s_addc_u32 s5, s5, 0
	s_add_u32 s6, s6, 0x10000
	s_addc_u32 s7, s7, 0
	global_load_dwordx4 v[156:159], v5, s[6:7]
	global_load_dwordx4 v[160:163], v5, s[6:7] offset:16
	global_load_dwordx4 v[164:167], v5, s[6:7] offset:32
	global_load_dwordx4 v[168:171], v5, s[6:7] offset:48
	global_load_dwordx4 v[172:175], v4, s[4:5]
	s_add_u32 s4, s4, 0x200000
	s_addc_u32 s5, s5, 0
	s_add_u32 s6, s6, 0x10000
	s_addc_u32 s7, s7, 0
	s_waitcnt vmcnt(28)
	v_add_f32_e32 v16, v16, v17
	v_add_f32_e32 v18, v18, v19
	v_add_f32_e32 v20, v20, v21
	v_add_f32_e32 v22, v22, v23
	v_add_f32_e32 v24, v24, v25
	v_add_f32_e32 v26, v26, v27
	v_add_f32_e32 v28, v28, v29
	v_add_f32_e32 v30, v30, v31
	v_add_f32_e32 v16, v16, v18
	v_add_f32_e32 v20, v20, v22
	v_add_f32_e32 v24, v24, v26
	v_add_f32_e32 v28, v28, v30
	v_add_f32_e32 v16, v16, v20
	v_add_f32_e32 v24, v24, v28
	v_add_f32_e32 v16, v16, v24
	v_fmamk_f32 v16, v16, 0x3a800000, v7
	v_rsq_f32_e32 v16, v16
	v_lshlrev_b32_e32 v20, 16, v32
	v_and_b32_e32 v21, 0xffff0000, v32
	v_lshlrev_b32_e32 v22, 16, v33
	v_and_b32_e32 v23, 0xffff0000, v33
	v_lshlrev_b32_e32 v24, 16, v34
	v_and_b32_e32 v25, 0xffff0000, v34
	v_lshlrev_b32_e32 v26, 16, v35
	v_and_b32_e32 v27, 0xffff0000, v35
	s_nop 0
	v_mul_f32_e32 v20, v16, v20
	v_mul_f32_e32 v21, v16, v21
	v_mul_f32_e32 v22, v16, v22
	v_mul_f32_e32 v23, v16, v23
	v_mul_f32_e32 v24, v16, v24
	v_mul_f32_e32 v25, v16, v25
	v_mul_f32_e32 v26, v16, v26
	v_mul_f32_e32 v27, v16, v27
	v_mul_f32_e32 v20, v8, v20
	v_mul_f32_e32 v21, v9, v21
	v_mul_f32_e32 v22, v10, v22
	v_mul_f32_e32 v23, v11, v23
	v_mul_f32_e32 v24, v12, v24
	v_mul_f32_e32 v25, v13, v25
	v_mul_f32_e32 v26, v14, v26
	v_mul_f32_e32 v27, v15, v27
	global_store_dwordx4 v6, v[20:23], s[8:9] nt
	global_store_dwordx4 v6, v[24:27], s[8:9] offset:16 nt
	s_add_u32 s8, s8, 0x400000
	s_addc_u32 s9, s9, 0
	v_add_f32_e32 v36, v36, v37
	v_add_f32_e32 v38, v38, v39
	v_add_f32_e32 v40, v40, v41
	v_add_f32_e32 v42, v42, v43
	v_add_f32_e32 v44, v44, v45
	v_add_f32_e32 v46, v46, v47
	v_add_f32_e32 v48, v48, v49
	v_add_f32_e32 v50, v50, v51
	v_add_f32_e32 v36, v36, v38
	v_add_f32_e32 v40, v40, v42
	v_add_f32_e32 v44, v44, v46
	v_add_f32_e32 v48, v48, v50
	v_add_f32_e32 v36, v36, v40
	v_add_f32_e32 v44, v44, v48
	v_add_f32_e32 v36, v36, v44
	v_fmamk_f32 v36, v36, 0x3a800000, v7
	v_rsq_f32_e32 v36, v36
	v_lshlrev_b32_e32 v40, 16, v52
	v_and_b32_e32 v41, 0xffff0000, v52
	v_lshlrev_b32_e32 v42, 16, v53
	v_and_b32_e32 v43, 0xffff0000, v53
	v_lshlrev_b32_e32 v44, 16, v54
	v_and_b32_e32 v45, 0xffff0000, v54
	v_lshlrev_b32_e32 v46, 16, v55
	v_and_b32_e32 v47, 0xffff0000, v55
	s_nop 0
	v_mul_f32_e32 v40, v36, v40
	v_mul_f32_e32 v41, v36, v41
	v_mul_f32_e32 v42, v36, v42
	v_mul_f32_e32 v43, v36, v43
	v_mul_f32_e32 v44, v36, v44
	v_mul_f32_e32 v45, v36, v45
	v_mul_f32_e32 v46, v36, v46
	v_mul_f32_e32 v47, v36, v47
	v_mul_f32_e32 v40, v8, v40
	v_mul_f32_e32 v41, v9, v41
	v_mul_f32_e32 v42, v10, v42
	v_mul_f32_e32 v43, v11, v43
	v_mul_f32_e32 v44, v12, v44
	v_mul_f32_e32 v45, v13, v45
	v_mul_f32_e32 v46, v14, v46
	v_mul_f32_e32 v47, v15, v47
	global_store_dwordx4 v6, v[40:43], s[8:9] nt
	global_store_dwordx4 v6, v[44:47], s[8:9] offset:16 nt
	s_add_u32 s8, s8, 0x400000
	s_addc_u32 s9, s9, 0
	v_add_f32_e32 v56, v56, v57
	v_add_f32_e32 v58, v58, v59
	v_add_f32_e32 v60, v60, v61
	v_add_f32_e32 v62, v62, v63
	v_add_f32_e32 v64, v64, v65
	v_add_f32_e32 v66, v66, v67
	v_add_f32_e32 v68, v68, v69
	v_add_f32_e32 v70, v70, v71
	v_add_f32_e32 v56, v56, v58
	v_add_f32_e32 v60, v60, v62
	v_add_f32_e32 v64, v64, v66
	v_add_f32_e32 v68, v68, v70
	v_add_f32_e32 v56, v56, v60
	v_add_f32_e32 v64, v64, v68
	v_add_f32_e32 v56, v56, v64
	v_fmamk_f32 v56, v56, 0x3a800000, v7
	v_rsq_f32_e32 v56, v56
	v_lshlrev_b32_e32 v60, 16, v72
	v_and_b32_e32 v61, 0xffff0000, v72
	v_lshlrev_b32_e32 v62, 16, v73
	v_and_b32_e32 v63, 0xffff0000, v73
	v_lshlrev_b32_e32 v64, 16, v74
	v_and_b32_e32 v65, 0xffff0000, v74
	v_lshlrev_b32_e32 v66, 16, v75
	v_and_b32_e32 v67, 0xffff0000, v75
	s_nop 0
	v_mul_f32_e32 v60, v56, v60
	v_mul_f32_e32 v61, v56, v61
	v_mul_f32_e32 v62, v56, v62
	v_mul_f32_e32 v63, v56, v63
	v_mul_f32_e32 v64, v56, v64
	v_mul_f32_e32 v65, v56, v65
	v_mul_f32_e32 v66, v56, v66
	v_mul_f32_e32 v67, v56, v67
	v_mul_f32_e32 v60, v8, v60
	v_mul_f32_e32 v61, v9, v61
	v_mul_f32_e32 v62, v10, v62
; __device__ __forceinline__ float bflo(unsigned w) { return __uint_as_float(w << 16); }
; __device__ __forceinline__ float bfhi(unsigned w) { return __uint_as_float(w & 0xffff0000u); }
; __device__ __forceinline__ float rstd_row(const float* ss, int row) { const f32x4* p = (const f32x4*)(ss + (size_t)row * 16); const f32x4 a = p[0], b = p[1], c = p[2], d = p[3];
;     const float s = (((a[0] + a[1]) + (a[2] + a[3])) + ((b[0] + b[1]) + (b[2] + b[3]))) + (((c[0] + c[1]) + (c[2] + c[3])) + ((d[0] + d[1]) + (d[2] + d[3]))); return __builtin_amdgcn_rsqf(s * (1.f / 1024.f) + EPS); }
; __device__ __forceinline__ void final_norm_phase(const Frame& F, const bf16* h, const float* ssq, const float* gain, float* out) {
;     for (int it = F.bx * NTHR + F.tid; it < M * 128; it += F.G * NTHR) { const int row = it >> 7, c8 = (it & 127) * 8; const float rs = rstd_row(ssq, row);
;         const v4u w = *(const v4u*)(h + (size_t)row * DM_ + c8); const f32x4 g0 = *(const f32x4*)(gain + c8), g1 = *(const f32x4*)(gain + c8 + 4);
;         float* o = out + (size_t)row * DM_ + c8;
;         __builtin_nontemporal_store((f32x4){bflo(w.x) * rs * g0[0], bfhi(w.x) * rs * g0[1], bflo(w.y) * rs * g0[2], bfhi(w.y) * rs * g0[3]}, (f32x4*)o);
;         __builtin_nontemporal_store((f32x4){bflo(w.z) * rs * g1[0], bfhi(w.z) * rs * g1[1], bflo(w.w) * rs * g1[2], bfhi(w.w) * rs * g1[3]}, (f32x4*)(o + 4)); }
	v_mul_f32_e32 v63, v11, v63
	v_mul_f32_e32 v64, v12, v64
	v_mul_f32_e32 v65, v13, v65
	v_mul_f32_e32 v66, v14, v66
	v_mul_f32_e32 v67, v15, v67
	global_store_dwordx4 v6, v[60:63], s[8:9] nt
	global_store_dwordx4 v6, v[64:67], s[8:9] offset:16 nt
	s_add_u32 s8, s8, 0x400000
	s_addc_u32 s9, s9, 0
	v_add_f32_e32 v76, v76, v77
	v_add_f32_e32 v78, v78, v79
	v_add_f32_e32 v80, v80, v81
	v_add_f32_e32 v82, v82, v83
	v_add_f32_e32 v84, v84, v85
	v_add_f32_e32 v86, v86, v87
	v_add_f32_e32 v88, v88, v89
	v_add_f32_e32 v90, v90, v91
	v_add_f32_e32 v76, v76, v78
	v_add_f32_e32 v80, v80, v82
	v_add_f32_e32 v84, v84, v86
	v_add_f32_e32 v88, v88, v90
	v_add_f32_e32 v76, v76, v80
	v_add_f32_e32 v84, v84, v88
	v_add_f32_e32 v76, v76, v84
	v_fmamk_f32 v76, v76, 0x3a800000, v7
	v_rsq_f32_e32 v76, v76
	v_lshlrev_b32_e32 v80, 16, v92
	v_and_b32_e32 v81, 0xffff0000, v92
	v_lshlrev_b32_e32 v82, 16, v93
	v_and_b32_e32 v83, 0xffff0000, v93
	v_lshlrev_b32_e32 v84, 16, v94
	v_and_b32_e32 v85, 0xffff0000, v94
	v_lshlrev_b32_e32 v86, 16, v95
	v_and_b32_e32 v87, 0xffff0000, v95
	s_nop 0
	v_mul_f32_e32 v80, v76, v80
	v_mul_f32_e32 v81, v76, v81
	v_mul_f32_e32 v82, v76, v82
	v_mul_f32_e32 v83, v76, v83
	v_mul_f32_e32 v84, v76, v84
	v_mul_f32_e32 v85, v76, v85
	v_mul_f32_e32 v86, v76, v86
	v_mul_f32_e32 v87, v76, v87
	v_mul_f32_e32 v80, v8, v80
	v_mul_f32_e32 v81, v9, v81
	v_mul_f32_e32 v82, v10, v82
	v_mul_f32_e32 v83, v11, v83
	v_mul_f32_e32 v84, v12, v84
	v_mul_f32_e32 v85, v13, v85
	v_mul_f32_e32 v86, v14, v86
	v_mul_f32_e32 v87, v15, v87
	global_store_dwordx4 v6, v[80:83], s[8:9] nt
	global_store_dwordx4 v6, v[84:87], s[8:9] offset:16 nt
	s_add_u32 s8, s8, 0x400000
	s_addc_u32 s9, s9, 0
	s_waitcnt vmcnt(8)
; __device__ __forceinline__ float bflo(unsigned w) { return __uint_as_float(w << 16); }
; __device__ __forceinline__ float bfhi(unsigned w) { return __uint_as_float(w & 0xffff0000u); }
; __device__ __forceinline__ void final_norm_phase(const Frame& F, const bf16* h, const float* ssq, const float* gain, float* out) {
;     for (int it = F.bx * NTHR + F.tid; it < M * 128; it += F.G * NTHR) { const int row = it >> 7, c8 = (it & 127) * 8; const float rs = rstd_row(ssq, row);
;         const v4u w = *(const v4u*)(h + (size_t)row * DM_ + c8); const f32x4 g0 = *(const f32x4*)(gain + c8), g1 = *(const f32x4*)(gain + c8 + 4);
;         float* o = out + (size_t)row * DM_ + c8;
;         __builtin_nontemporal_store((f32x4){bflo(w.x) * rs * g0[0], bfhi(w.x) * rs * g0[1], bflo(w.y) * rs * g0[2], bfhi(w.y) * rs * g0[3]}, (f32x4*)o);
;         __builtin_nontemporal_store((f32x4){bflo(w.z) * rs * g1[0], bfhi(w.z) * rs * g1[1], bflo(w.w) * rs * g1[2], bfhi(w.w) * rs * g1[3]}, (f32x4*)(o + 4)); }
	v_add_f32_e32 v96, v96, v97
	v_add_f32_e32 v98, v98, v99
	v_add_f32_e32 v100, v100, v101
	v_add_f32_e32 v102, v102, v103
	v_add_f32_e32 v104, v104, v105
	v_add_f32_e32 v106, v106, v107
	v_add_f32_e32 v108, v108, v109
	v_add_f32_e32 v110, v110, v111
	v_add_f32_e32 v96, v96, v98
	v_add_f32_e32 v100, v100, v102
	v_add_f32_e32 v104, v104, v106
	v_add_f32_e32 v108, v108, v110
	v_add_f32_e32 v96, v96, v100
	v_add_f32_e32 v104, v104, v108
	v_add_f32_e32 v96, v96, v104
	v_fmamk_f32 v96, v96, 0x3a800000, v7
	v_rsq_f32_e32 v96, v96
	v_lshlrev_b32_e32 v100, 16, v112
	v_and_b32_e32 v101, 0xffff0000, v112
	v_lshlrev_b32_e32 v102, 16, v113
	v_and_b32_e32 v103, 0xffff0000, v113
	v_lshlrev_b32_e32 v104, 16, v114
	v_and_b32_e32 v105, 0xffff0000, v114
	v_lshlrev_b32_e32 v106, 16, v115
	v_and_b32_e32 v107, 0xffff0000, v115
	s_nop 0
	v_mul_f32_e32 v100, v96, v100
	v_mul_f32_e32 v101, v96, v101
	v_mul_f32_e32 v102, v96, v102
	v_mul_f32_e32 v103, v96, v103
	v_mul_f32_e32 v104, v96, v104
	v_mul_f32_e32 v105, v96, v105
	v_mul_f32_e32 v106, v96, v106
	v_mul_f32_e32 v107, v96, v107
	v_mul_f32_e32 v100, v8, v100
	v_mul_f32_e32 v101, v9, v101
	v_mul_f32_e32 v102, v10, v102
	v_mul_f32_e32 v103, v11, v103
	v_mul_f32_e32 v104, v12, v104
	v_mul_f32_e32 v105, v13, v105
	v_mul_f32_e32 v106, v14, v106
	v_mul_f32_e32 v107, v15, v107
	global_store_dwordx4 v6, v[100:103], s[8:9] nt
	global_store_dwordx4 v6, v[104:107], s[8:9] offset:16 nt
	s_add_u32 s8, s8, 0x400000
	s_addc_u32 s9, s9, 0
	v_add_f32_e32 v116, v116, v117
	v_add_f32_e32 v118, v118, v119
	v_add_f32_e32 v120, v120, v121
	v_add_f32_e32 v122, v122, v123
	v_add_f32_e32 v124, v124, v125
	v_add_f32_e32 v126, v126, v127
	v_add_f32_e32 v128, v128, v129
	v_add_f32_e32 v130, v130, v131
	v_add_f32_e32 v116, v116, v118
	v_add_f32_e32 v120, v120, v122
	v_add_f32_e32 v124, v124, v126
	v_add_f32_e32 v128, v128, v130
	v_add_f32_e32 v116, v116, v120
	v_add_f32_e32 v124, v124, v128
	v_add_f32_e32 v116, v116, v124
	v_fmamk_f32 v116, v116, 0x3a800000, v7
	v_rsq_f32_e32 v116, v116
	v_lshlrev_b32_e32 v120, 16, v132
	v_and_b32_e32 v121, 0xffff0000, v132
	v_lshlrev_b32_e32 v122, 16, v133
	v_and_b32_e32 v123, 0xffff0000, v133
	v_lshlrev_b32_e32 v124, 16, v134
	v_and_b32_e32 v125, 0xffff0000, v134
	v_lshlrev_b32_e32 v126, 16, v135
	v_and_b32_e32 v127, 0xffff0000, v135
	s_nop 0
	v_mul_f32_e32 v120, v116, v120
	v_mul_f32_e32 v121, v116, v121
	v_mul_f32_e32 v122, v116, v122
	v_mul_f32_e32 v123, v116, v123
	v_mul_f32_e32 v124, v116, v124
	v_mul_f32_e32 v125, v116, v125
	v_mul_f32_e32 v126, v116, v126
	v_mul_f32_e32 v127, v116, v127
	v_mul_f32_e32 v120, v8, v120
	v_mul_f32_e32 v121, v9, v121
	v_mul_f32_e32 v122, v10, v122
	v_mul_f32_e32 v123, v11, v123
	v_mul_f32_e32 v124, v12, v124
	v_mul_f32_e32 v125, v13, v125
	v_mul_f32_e32 v126, v14, v126
	v_mul_f32_e32 v127, v15, v127
	global_store_dwordx4 v6, v[120:123], s[8:9] nt
	global_store_dwordx4 v6, v[124:127], s[8:9] offset:16 nt
	s_add_u32 s8, s8, 0x400000
	s_addc_u32 s9, s9, 0
	v_add_f32_e32 v136, v136, v137
	v_add_f32_e32 v138, v138, v139
	v_add_f32_e32 v140, v140, v141
	v_add_f32_e32 v142, v142, v143
	v_add_f32_e32 v144, v144, v145
	v_add_f32_e32 v146, v146, v147
	v_add_f32_e32 v148, v148, v149
	v_add_f32_e32 v150, v150, v151
	v_add_f32_e32 v136, v136, v138
	v_add_f32_e32 v140, v140, v142
	v_add_f32_e32 v144, v144, v146
	v_add_f32_e32 v148, v148, v150
	v_add_f32_e32 v136, v136, v140
	v_add_f32_e32 v144, v144, v148
	v_add_f32_e32 v136, v136, v144
	v_fmamk_f32 v136, v136, 0x3a800000, v7
	v_rsq_f32_e32 v136, v136
	v_lshlrev_b32_e32 v140, 16, v152
	v_and_b32_e32 v141, 0xffff0000, v152
	v_lshlrev_b32_e32 v142, 16, v153
	v_and_b32_e32 v143, 0xffff0000, v153
	v_lshlrev_b32_e32 v144, 16, v154
	v_and_b32_e32 v145, 0xffff0000, v154
	v_lshlrev_b32_e32 v146, 16, v155
	v_and_b32_e32 v147, 0xffff0000, v155
	s_nop 0
	v_mul_f32_e32 v140, v136, v140
	v_mul_f32_e32 v141, v136, v141
	v_mul_f32_e32 v142, v136, v142
	v_mul_f32_e32 v143, v136, v143
	v_mul_f32_e32 v144, v136, v144
	v_mul_f32_e32 v145, v136, v145
	v_mul_f32_e32 v146, v136, v146
	v_mul_f32_e32 v147, v136, v147
	v_mul_f32_e32 v140, v8, v140
	v_mul_f32_e32 v141, v9, v141
	v_mul_f32_e32 v142, v10, v142
	v_mul_f32_e32 v143, v11, v143
	v_mul_f32_e32 v144, v12, v144
	v_mul_f32_e32 v145, v13, v145
	v_mul_f32_e32 v146, v14, v146
	v_mul_f32_e32 v147, v15, v147
	global_store_dwordx4 v6, v[140:143], s[8:9] nt
	global_store_dwordx4 v6, v[144:147], s[8:9] offset:16 nt
	s_add_u32 s8, s8, 0x400000
	s_addc_u32 s9, s9, 0
	v_add_f32_e32 v156, v156, v157
	v_add_f32_e32 v158, v158, v159
	v_add_f32_e32 v160, v160, v161
	v_add_f32_e32 v162, v162, v163
	v_add_f32_e32 v164, v164, v165
	v_add_f32_e32 v166, v166, v167
	v_add_f32_e32 v168, v168, v169
	v_add_f32_e32 v170, v170, v171
	v_add_f32_e32 v156, v156, v158
	v_add_f32_e32 v160, v160, v162
	v_add_f32_e32 v164, v164, v166
	v_add_f32_e32 v168, v168, v170
	v_add_f32_e32 v156, v156, v160
	v_add_f32_e32 v164, v164, v168
	v_add_f32_e32 v156, v156, v164
	v_fmamk_f32 v156, v156, 0x3a800000, v7
	v_rsq_f32_e32 v156, v156
	v_lshlrev_b32_e32 v160, 16, v172
	v_and_b32_e32 v161, 0xffff0000, v172
	v_lshlrev_b32_e32 v162, 16, v173
	v_and_b32_e32 v163, 0xffff0000, v173
	v_lshlrev_b32_e32 v164, 16, v174
	v_and_b32_e32 v165, 0xffff0000, v174
	v_lshlrev_b32_e32 v166, 16, v175
	v_and_b32_e32 v167, 0xffff0000, v175
	s_nop 0
	v_mul_f32_e32 v160, v156, v160
	v_mul_f32_e32 v161, v156, v161
	v_mul_f32_e32 v162, v156, v162
	v_mul_f32_e32 v163, v156, v163
	v_mul_f32_e32 v164, v156, v164
	v_mul_f32_e32 v165, v156, v165
	v_mul_f32_e32 v166, v156, v166
	v_mul_f32_e32 v167, v156, v167
	v_mul_f32_e32 v160, v8, v160
	v_mul_f32_e32 v161, v9, v161
	v_mul_f32_e32 v162, v10, v162
	v_mul_f32_e32 v163, v11, v163
	v_mul_f32_e32 v164, v12, v164
	v_mul_f32_e32 v165, v13, v165
	v_mul_f32_e32 v166, v14, v166
	v_mul_f32_e32 v167, v15, v167
	global_store_dwordx4 v6, v[160:163], s[8:9] nt
	global_store_dwordx4 v6, v[164:167], s[8:9] offset:16 nt
	s_add_u32 s8, s8, 0x400000
	s_addc_u32 s9, s9, 0
	s_endpgm
.Lfn_orig:
	s_mov_b32 s0, 0x400000
	v_lshl_add_u32 v2, s96, 9, v0
	s_mov_b32 s8, 28
	v_cmp_gt_i32_e32 vcc, s0, v2
	s_and_saveexec_b64 s[0:1], vcc
	s_cbranch_execz .LBB0_1845
	s_waitcnt lgkmcnt(0)
	s_add_u32 s4, s78, 0x7c00000
	s_addc_u32 s5, s79, 0
	s_add_u32 s6, s78, 0x5800000
	s_addc_u32 s7, s79, 0
	s_ashr_i32 s9, s8, 31
	s_lshl_b64 s[0:1], s[8:9], 3
	s_add_u32 s0, s74, s0
	s_addc_u32 s1, s75, s1
	s_load_dwordx2 s[0:1], s[0:1], 0x0
	v_lshlrev_b32_e32 v0, 3, v0
	s_lshl_b32 s8, s82, 9
	v_lshl_add_u32 v3, s96, 12, v0
	s_lshl_b32 s9, s82, 12
	s_mov_b64 s[2:3], 0
	v_mov_b32_e32 v4, 0x358637bd
	v_mov_b32_e32 v1, 0
	s_mov_b32 s10, 0x3fffff
